# LDS-DMA (global_load_lds) K/V tile staging in mode-0 attention loop; no VGPR staging or ds_write
# speedup vs baseline: 1.0749x; 1.0150x over previous
; template <int MODE>
; __device__ __forceinline__ void attn_body(const bf16_t* __restrict__ Qb, const bf16_t* __restrict__ Kh, const bf16_t* __restrict__ Vh, int NT, int krel0,
;                                           char* lds, const float* __restrict__ lutg, const AttnEpi& E) {
;     ...
;   const bf16_t* Qw = Qb + (size_t)(wid * 32 + r32) * LDQK + hi * 8;
;   {
;     float qf[ND0][8]; float ss = 0.f;
; #pragma unroll
;     for (int d0 = 0; d0 < ND0; ++d0) { const bf16x8 raw = *reinterpret_cast<const bf16x8*>(Qw + d0 * 16);
; #pragma unroll
;       for (int j = 0; j < 8; ++j) { const float v = __uint_as_float(((unsigned)(unsigned short)raw[j]) << 16); qf[d0][j] = v; ss += v * v; } }
;     { auto rr = __builtin_amdgcn_permlane32_swap(__float_as_uint(ss), __float_as_uint(ss), false, false);
;       ss = __uint_as_float(rr[0]) + __uint_as_float(rr[1]); }
;     const float rs = rsqrtf(ss * (MODE < 2 ? (1.f / 128.f) : (1.f / 64.f)) + EPS);
; #pragma unroll
;     for (int d0 = 0; d0 < ND0; ++d0) { const f32x4 g0 = *(const f32x4*)(E.gq + d0 * 16 + hi * 8), g1 = *(const f32x4*)(E.gq + d0 * 16 + hi * 8 + 4);
; #pragma unroll
;       for (int j = 0; j < 4; ++j) { qf[d0][j] = qf[d0][j] * rs * g0[j]; qf[d0][4 + j] = qf[d0][4 + j] * rs * g1[j]; } }
;     if constexpr (MODE == 0) {
;       const int sp = krel0 + wid * 32 + r32;
; #pragma unroll
;       for (int h = 0; h < 2; ++h) { const int pos = h == 0 ? (sp >> 6) : (sp & 63);
; #pragma unroll
;         for (int a = 0; a < 2; ++a) { const float* tb = lutg + (size_t)(pos * 32 + a * 16 + hi * 8) * 2;
; #pragma unroll
;           for (int jj = 0; jj < 4; ++jj) { const f32x4 cs = *(const f32x4*)(tb + jj * 4);
.LBB0_78:
	s_lshl_b32 s64, s58, 8
	s_and_b32 s0, s93, 4
	s_add_i32 s54, s2, s64
	s_lshl_b32 s84, s0, 6
	s_and_b32 s59, s10, 7
	s_ashr_i32 s55, s54, 31
	s_mul_i32 s1, s54, 0x2400
	v_readlane_b32 s6, v252, 6
	s_mul_hi_i32 s0, s54, 0x2400
	v_readlane_b32 s7, v252, 7
	s_add_u32 s17, s6, s1
	s_addc_u32 s18, s7, s0
	s_mul_i32 s1, s2, 0x2400
	s_mul_hi_u32 s0, s2, 0x2400
	s_add_u32 s67, s6, s1
	s_addc_u32 s65, s7, s0
	v_readlane_b32 s0, v255, 7
	s_or_b32 s0, s59, s0
	s_ashr_i32 s1, s0, 31
	v_readlane_b32 s68, v254, 41
	s_lshl_b32 s63, s59, 7
	s_lshl_b64 s[0:1], s[0:1], 2
	v_readlane_b32 s70, v254, 43
	v_readlane_b32 s71, v254, 44
	s_add_u32 s0, s70, s0
	s_addc_u32 s1, s71, s1
	global_load_dword v184, v1, s[0:1]
	s_lshl_b32 s0, s59, 8
	s_add_u32 s60, s17, s0
	v_mov_b32_e32 v188, v179
	s_addc_u32 s61, s18, 0
	s_movk_i32 s6, 0xffe0
	v_ashrrev_i32_e32 v4, 1, v188
	v_bfe_u32 v164, v188, 5, 1
	v_bfi_b32 v0, s6, v4, v188
	v_mov_b64_e32 v[2:3], s[60:61]
	s_movk_i32 s56, 0x2400
	v_mad_i64_i32 v[2:3], s[0:1], v0, s56, v[2:3]
	v_lshlrev_b32_e32 v0, 4, v164
	v_lshl_add_u64 v[2:3], v[2:3], 0, v[0:1]
	s_waitcnt lgkmcnt(0)
	s_barrier
	global_load_dwordx4 v[22:25], v[2:3], off offset:160
	global_load_dwordx4 v[48:51], v[2:3], off offset:224
	global_load_dwordx4 v[124:127], v[2:3], off offset:128
	global_load_dwordx4 v[128:131], v[2:3], off offset:192
	global_load_dwordx4 v[166:169], v[2:3], off
	global_load_dwordx4 v[170:173], v[2:3], off offset:32
	global_load_dwordx4 v[174:177], v[2:3], off offset:64
	global_load_dwordx4 v[206:209], v[2:3], off offset:96
	v_and_b32_e32 v2, 32, v188
	global_load_dwordx4 v[120:123], v2, s[12:13]
	global_load_dwordx4 v[116:119], v2, s[12:13] offset:16
	global_load_dwordx4 v[112:115], v2, s[12:13] offset:64
	global_load_dwordx4 v[108:111], v2, s[12:13] offset:80
	global_load_dwordx4 v[104:107], v2, s[12:13] offset:128
	global_load_dwordx4 v[100:103], v2, s[12:13] offset:144
	global_load_dwordx4 v[96:99], v2, s[12:13] offset:192
	global_load_dwordx4 v[92:95], v2, s[12:13] offset:208
	global_load_dwordx4 v[88:91], v2, s[12:13] offset:256
	global_load_dwordx4 v[84:87], v2, s[12:13] offset:272
	global_load_dwordx4 v[80:83], v2, s[12:13] offset:320
	global_load_dwordx4 v[76:79], v2, s[12:13] offset:336
	global_load_dwordx4 v[68:71], v2, s[12:13] offset:384
	global_load_dwordx4 v[64:67], v2, s[12:13] offset:400
	global_load_dwordx4 v[60:63], v2, s[12:13] offset:448
	global_load_dwordx4 v[52:55], v2, s[12:13] offset:464
	v_and_b32_e32 v189, 31, v188
	s_lshl_b32 s0, s10, 5
	v_and_b32_e32 v204, 0xffffffe0, v4
	v_or_b32_e32 v2, s64, v189
	s_and_b32 s62, s0, 0x80
	v_add_u32_e32 v7, v2, v204
	s_lshl_b32 s0, s62, 1
	v_lshlrev_b32_e32 v6, 3, v164
	v_ashrrev_i32_e32 v2, 1, v7
	s_add_u32 s0, s67, s0
	v_and_or_b32 v2, v2, s6, v6
	s_addc_u32 s1, s65, 0
	v_and_b32_e32 v5, 0x3fffffc0, v188
	s_add_i32 s89, 0, 0x18000
	v_ashrrev_i32_e32 v3, 31, v2
	v_lshl_add_u32 v163, v5, 2, s89
	v_lshl_add_u64 v[4:5], v[2:3], 3, s[96:97]
	global_load_dwordx4 v[30:33], v[4:5], off offset:48
	global_load_dwordx4 v[38:41], v[4:5], off offset:32
	global_load_dwordx4 v[56:59], v[4:5], off offset:16
	global_load_dwordx4 v[72:75], v[4:5], off
	v_or_b32_e32 v2, 16, v2
	v_ashrrev_i32_e32 v3, 31, v2
	v_lshl_add_u64 v[2:3], v[2:3], 3, s[96:97]
	global_load_dwordx4 v[18:21], v[2:3], off offset:48
	global_load_dwordx4 v[26:29], v[2:3], off offset:32
	global_load_dwordx4 v[34:37], v[2:3], off offset:16
	global_load_dwordx4 v[42:45], v[2:3], off
	v_lshlrev_b32_e32 v2, 5, v7
	s_movk_i32 s6, 0x7e0
	v_and_or_b32 v2, v2, s6, v6
	v_lshlrev_b32_e32 v165, 3, v2
	global_load_dwordx4 v[2:5], v165, s[96:97] offset:48
	global_load_dwordx4 v[6:9], v165, s[96:97] offset:32
	global_load_dwordx4 v[10:13], v165, s[96:97] offset:16
	global_load_dwordx4 v[14:17], v165, s[96:97]
	s_movk_i32 s57, 0x1200
	v_and_b32_e32 v162, 63, v188
	s_cmp_lg_u32 0, -1
	v_readlane_b32 s69, v254, 42
	s_mov_b32 s68, 0
	v_readlane_b32 s72, v254, 45
	v_readlane_b32 s73, v254, 46
	v_readlane_b32 s74, v254, 47
	v_readlane_b32 s75, v254, 48
	v_readlane_b32 s76, v254, 49
	v_readlane_b32 s77, v254, 50
	v_readlane_b32 s78, v254, 51
	v_readlane_b32 s79, v254, 52
	v_readlane_b32 s80, v254, 53
	v_readlane_b32 s81, v254, 54
	v_readlane_b32 s82, v254, 55
	v_readlane_b32 s83, v254, 56
	s_mov_b32 s69, s68
	s_mov_b32 s70, s68
	s_mov_b32 s71, s68
	s_mov_b32 s72, s68
	s_mov_b32 s73, s68
	s_mov_b32 s74, s68
	s_mov_b32 s75, s68
	s_mov_b32 s76, s68
	s_mov_b32 s77, s68
	s_mov_b32 s78, s68
	s_mov_b32 s79, s68
	s_mov_b32 s80, s68
	s_mov_b32 s81, s68
	s_mov_b32 s82, s68
	s_mov_b32 s83, s68
	s_mov_b32 s66, 4
	s_waitcnt vmcnt(35)
	v_and_b32_e32 v147, 0xffff0000, v22
	s_waitcnt vmcnt(31)
	v_and_b32_e32 v221, 0xffff0000, v167
	v_lshlrev_b32_e32 v220, 16, v167
	v_and_b32_e32 v167, 0xffff0000, v166
	v_lshlrev_b32_e32 v146, 16, v22
	v_lshlrev_b32_e32 v166, 16, v166
	v_mul_f32_e32 v22, v167, v167
	v_and_b32_e32 v141, 0xffff0000, v23
	v_lshlrev_b32_e32 v140, 16, v23
	v_pk_fma_f32 v[22:23], v[166:167], v[166:167], v[22:23] op_sel_hi:[1,1,0]
	v_and_b32_e32 v139, 0xffff0000, v24
	v_lshlrev_b32_e32 v138, 16, v24
	v_pk_fma_f32 v[22:23], v[220:221], v[220:221], v[22:23]
	v_mul_f32_e32 v24, v221, v221
	v_and_b32_e32 v217, 0xffff0000, v169
	v_lshlrev_b32_e32 v216, 16, v169
	v_and_b32_e32 v169, 0xffff0000, v168
	v_lshlrev_b32_e32 v168, 16, v168
	v_pk_add_f32 v[22:23], v[24:25], v[22:23] op_sel_hi:[0,1]
	v_pk_fma_f32 v[22:23], v[168:169], v[168:169], v[22:23]
	v_mul_f32_e32 v24, v169, v169
	v_pk_add_f32 v[22:23], v[24:25], v[22:23] op_sel_hi:[0,1]
	v_pk_fma_f32 v[22:23], v[216:217], v[216:217], v[22:23]
	v_mul_f32_e32 v24, v217, v217
	s_waitcnt vmcnt(30)
; template <int MODE>
; __device__ __forceinline__ void attn_body(const bf16_t* __restrict__ Qb, const bf16_t* __restrict__ Kh, const bf16_t* __restrict__ Vh, int NT, int krel0,
;                                           char* lds, const float* __restrict__ lutg, const AttnEpi& E) {
;     ...
;     float qf[ND0][8]; float ss = 0.f;
; #pragma unroll
;     for (int d0 = 0; d0 < ND0; ++d0) { const bf16x8 raw = *reinterpret_cast<const bf16x8*>(Qw + d0 * 16);
; #pragma unroll
;       for (int j = 0; j < 8; ++j) { const float v = __uint_as_float(((unsigned)(unsigned short)raw[j]) << 16); qf[d0][j] = v; ss += v * v; } }
;     { auto rr = __builtin_amdgcn_permlane32_swap(__float_as_uint(ss), __float_as_uint(ss), false, false);
;       ss = __uint_as_float(rr[0]) + __uint_as_float(rr[1]); }
;     const float rs = rsqrtf(ss * (MODE < 2 ? (1.f / 128.f) : (1.f / 64.f)) + EPS);
	v_and_b32_e32 v213, 0xffff0000, v171
	v_lshlrev_b32_e32 v212, 16, v171
	v_and_b32_e32 v171, 0xffff0000, v170
	v_lshlrev_b32_e32 v170, 16, v170
	v_pk_add_f32 v[22:23], v[24:25], v[22:23] op_sel_hi:[0,1]
	v_pk_fma_f32 v[22:23], v[170:171], v[170:171], v[22:23]
	v_mul_f32_e32 v24, v171, v171
	v_pk_add_f32 v[22:23], v[24:25], v[22:23] op_sel_hi:[0,1]
	v_pk_fma_f32 v[22:23], v[212:213], v[212:213], v[22:23]
	v_mul_f32_e32 v24, v213, v213
	v_and_b32_e32 v191, 0xffff0000, v173
	v_lshlrev_b32_e32 v190, 16, v173
	v_and_b32_e32 v173, 0xffff0000, v172
	v_lshlrev_b32_e32 v172, 16, v172
	v_pk_add_f32 v[22:23], v[24:25], v[22:23] op_sel_hi:[0,1]
	v_pk_fma_f32 v[22:23], v[172:173], v[172:173], v[22:23]
	v_mul_f32_e32 v24, v173, v173
	v_pk_add_f32 v[22:23], v[24:25], v[22:23] op_sel_hi:[0,1]
	v_pk_fma_f32 v[22:23], v[190:191], v[190:191], v[22:23]
	v_mul_f32_e32 v24, v191, v191
	s_waitcnt vmcnt(29)
	v_and_b32_e32 v223, 0xffff0000, v175
	v_lshlrev_b32_e32 v222, 16, v175
	v_and_b32_e32 v175, 0xffff0000, v174
	v_lshlrev_b32_e32 v174, 16, v174
	v_pk_add_f32 v[22:23], v[24:25], v[22:23] op_sel_hi:[0,1]
	v_pk_fma_f32 v[22:23], v[174:175], v[174:175], v[22:23]
	v_mul_f32_e32 v24, v175, v175
	v_pk_add_f32 v[22:23], v[24:25], v[22:23] op_sel_hi:[0,1]
	v_pk_fma_f32 v[22:23], v[222:223], v[222:223], v[22:23]
	v_mul_f32_e32 v24, v223, v223
	v_and_b32_e32 v219, 0xffff0000, v177
	v_lshlrev_b32_e32 v218, 16, v177
	v_and_b32_e32 v177, 0xffff0000, v176
	v_lshlrev_b32_e32 v176, 16, v176
	v_pk_add_f32 v[22:23], v[24:25], v[22:23] op_sel_hi:[0,1]
	v_pk_fma_f32 v[22:23], v[176:177], v[176:177], v[22:23]
	v_mul_f32_e32 v24, v177, v177
	v_pk_add_f32 v[22:23], v[24:25], v[22:23] op_sel_hi:[0,1]
	v_pk_fma_f32 v[22:23], v[218:219], v[218:219], v[22:23]
	v_mul_f32_e32 v24, v219, v219
	s_waitcnt vmcnt(28)
	v_and_b32_e32 v215, 0xffff0000, v207
	v_lshlrev_b32_e32 v214, 16, v207
	v_and_b32_e32 v207, 0xffff0000, v206
	v_lshlrev_b32_e32 v206, 16, v206
	v_pk_add_f32 v[22:23], v[24:25], v[22:23] op_sel_hi:[0,1]
	v_pk_fma_f32 v[22:23], v[206:207], v[206:207], v[22:23]
	v_mul_f32_e32 v24, v207, v207
	v_pk_add_f32 v[22:23], v[24:25], v[22:23] op_sel_hi:[0,1]
	v_pk_fma_f32 v[22:23], v[214:215], v[214:215], v[22:23]
	v_mul_f32_e32 v24, v215, v215
	v_and_b32_e32 v211, 0xffff0000, v209
	v_lshlrev_b32_e32 v210, 16, v209
	v_and_b32_e32 v209, 0xffff0000, v208
	v_lshlrev_b32_e32 v208, 16, v208
	v_pk_add_f32 v[22:23], v[24:25], v[22:23] op_sel_hi:[0,1]
	v_pk_fma_f32 v[22:23], v[208:209], v[208:209], v[22:23]
	v_mul_f32_e32 v24, v209, v209
	v_pk_add_f32 v[22:23], v[24:25], v[22:23] op_sel_hi:[0,1]
	v_pk_fma_f32 v[22:23], v[210:211], v[210:211], v[22:23]
	v_mul_f32_e32 v24, v211, v211
	v_and_b32_e32 v161, 0xffff0000, v124
	v_lshlrev_b32_e32 v160, 16, v124
	v_pk_add_f32 v[22:23], v[24:25], v[22:23] op_sel_hi:[0,1]
	v_pk_fma_f32 v[22:23], v[160:161], v[160:161], v[22:23]
	v_mul_f32_e32 v24, v161, v161
	v_and_b32_e32 v157, 0xffff0000, v125
	v_lshlrev_b32_e32 v156, 16, v125
	v_pk_add_f32 v[22:23], v[24:25], v[22:23] op_sel_hi:[0,1]
	v_pk_fma_f32 v[22:23], v[156:157], v[156:157], v[22:23]
	v_mul_f32_e32 v24, v157, v157
	v_and_b32_e32 v155, 0xffff0000, v126
	v_lshlrev_b32_e32 v154, 16, v126
	v_pk_add_f32 v[22:23], v[24:25], v[22:23] op_sel_hi:[0,1]
	v_pk_fma_f32 v[22:23], v[154:155], v[154:155], v[22:23]
	v_mul_f32_e32 v24, v155, v155
	v_and_b32_e32 v149, 0xffff0000, v127
	v_lshlrev_b32_e32 v148, 16, v127
	v_pk_add_f32 v[22:23], v[24:25], v[22:23] op_sel_hi:[0,1]
	v_pk_fma_f32 v[22:23], v[148:149], v[148:149], v[22:23]
	v_mul_f32_e32 v24, v149, v149
	v_pk_add_f32 v[22:23], v[24:25], v[22:23] op_sel_hi:[0,1]
	v_pk_fma_f32 v[22:23], v[146:147], v[146:147], v[22:23]
	v_mul_f32_e32 v24, v147, v147
	v_pk_add_f32 v[22:23], v[24:25], v[22:23] op_sel_hi:[0,1]
	v_pk_fma_f32 v[22:23], v[140:141], v[140:141], v[22:23]
	v_mul_f32_e32 v24, v141, v141
	v_pk_add_f32 v[22:23], v[24:25], v[22:23] op_sel_hi:[0,1]
	v_pk_fma_f32 v[22:23], v[138:139], v[138:139], v[22:23]
	v_mul_f32_e32 v24, v139, v139
	v_and_b32_e32 v133, 0xffff0000, v25
	v_lshlrev_b32_e32 v132, 16, v25
	v_pk_add_f32 v[22:23], v[24:25], v[22:23] op_sel_hi:[0,1]
	v_pk_fma_f32 v[22:23], v[132:133], v[132:133], v[22:23]
	v_mul_f32_e32 v24, v133, v133
	v_and_b32_e32 v159, 0xffff0000, v128
	v_lshlrev_b32_e32 v158, 16, v128
	v_pk_add_f32 v[22:23], v[24:25], v[22:23] op_sel_hi:[0,1]
	v_pk_fma_f32 v[22:23], v[158:159], v[158:159], v[22:23]
	v_mul_f32_e32 v24, v159, v159
	v_and_b32_e32 v153, 0xffff0000, v129
	v_lshlrev_b32_e32 v152, 16, v129
	v_pk_add_f32 v[22:23], v[24:25], v[22:23] op_sel_hi:[0,1]
	v_pk_fma_f32 v[22:23], v[152:153], v[152:153], v[22:23]
	v_mul_f32_e32 v24, v153, v153
	v_and_b32_e32 v151, 0xffff0000, v130
	v_lshlrev_b32_e32 v150, 16, v130
	v_pk_add_f32 v[22:23], v[24:25], v[22:23] op_sel_hi:[0,1]
	v_pk_fma_f32 v[22:23], v[150:151], v[150:151], v[22:23]
	v_mul_f32_e32 v24, v151, v151
	v_and_b32_e32 v145, 0xffff0000, v131
	v_lshlrev_b32_e32 v144, 16, v131
	v_pk_add_f32 v[22:23], v[24:25], v[22:23] op_sel_hi:[0,1]
	v_pk_fma_f32 v[22:23], v[144:145], v[144:145], v[22:23]
	v_mul_f32_e32 v24, v145, v145
	v_and_b32_e32 v143, 0xffff0000, v48
	v_lshlrev_b32_e32 v142, 16, v48
	v_pk_add_f32 v[22:23], v[24:25], v[22:23] op_sel_hi:[0,1]
	v_pk_fma_f32 v[22:23], v[142:143], v[142:143], v[22:23]
	v_mul_f32_e32 v24, v143, v143
	v_and_b32_e32 v137, 0xffff0000, v49
	v_lshlrev_b32_e32 v136, 16, v49
	v_pk_add_f32 v[22:23], v[24:25], v[22:23] op_sel_hi:[0,1]
	v_pk_fma_f32 v[22:23], v[136:137], v[136:137], v[22:23]
	v_mul_f32_e32 v24, v137, v137
	v_and_b32_e32 v135, 0xffff0000, v50
	v_lshlrev_b32_e32 v134, 16, v50
	v_pk_add_f32 v[22:23], v[24:25], v[22:23] op_sel_hi:[0,1]
	v_pk_fma_f32 v[22:23], v[134:135], v[134:135], v[22:23]
	v_mul_f32_e32 v24, v135, v135
	v_and_b32_e32 v47, 0xffff0000, v51
	v_lshlrev_b32_e32 v46, 16, v51
	v_pk_add_f32 v[22:23], v[24:25], v[22:23] op_sel_hi:[0,1]
	v_pk_fma_f32 v[22:23], v[46:47], v[46:47], v[22:23]
	v_mul_f32_e32 v24, v47, v47
	v_pk_add_f32 v[22:23], v[24:25], v[22:23] op_sel_hi:[0,1]
	v_mov_b32_e32 v23, v22
	s_nop 1
	v_permlane32_swap_b32_e32 v22, v23
	v_add_f32_e32 v22, v22, v23
	v_fmamk_f32 v22, v22, 0x3c000000, v178
	v_mul_f32_e32 v23, 0x4b800000, v22
	v_cmp_gt_f32_e32 vcc, s49, v22
	s_nop 1
	v_cndmask_b32_e32 v22, v22, v23, vcc
	v_rsq_f32_e32 v205, v22
	global_load_dwordx4 v[22:25], v165, s[96:97] offset:176
	global_load_dwordx4 v[48:51], v165, s[96:97] offset:160
	global_load_dwordx4 v[124:127], v165, s[96:97] offset:144
	global_load_dwordx4 v[128:131], v165, s[96:97] offset:128
	v_mul_f32_e32 v165, 0x45800000, v205
	v_cndmask_b32_e32 v224, v205, v165, vcc
	v_pk_mul_f32 v[166:167], v[224:225], v[166:167] op_sel_hi:[0,1]
	s_waitcnt vmcnt(31)
; template <int MODE>
; __device__ __forceinline__ void attn_body(const bf16_t* __restrict__ Qb, const bf16_t* __restrict__ Kh, const bf16_t* __restrict__ Vh, int NT, int krel0,
;                                           char* lds, const float* __restrict__ lutg, const AttnEpi& E) {
;     ...
; #pragma unroll
;     for (int d0 = 0; d0 < ND0; ++d0) { const f32x4 g0 = *(const f32x4*)(E.gq + d0 * 16 + hi * 8), g1 = *(const f32x4*)(E.gq + d0 * 16 + hi * 8 + 4);
; #pragma unroll
;       for (int j = 0; j < 4; ++j) { qf[d0][j] = qf[d0][j] * rs * g0[j]; qf[d0][4 + j] = qf[d0][4 + j] * rs * g1[j]; } }
;     if constexpr (MODE == 0) {
;       const int sp = krel0 + wid * 32 + r32;
; #pragma unroll
;       for (int h = 0; h < 2; ++h) { const int pos = h == 0 ? (sp >> 6) : (sp & 63);
; #pragma unroll
;         for (int a = 0; a < 2; ++a) { const float* tb = lutg + (size_t)(pos * 32 + a * 16 + hi * 8) * 2;
; #pragma unroll
;           for (int jj = 0; jj < 4; ++jj) { const f32x4 cs = *(const f32x4*)(tb + jj * 4);
; #pragma unroll
;             for (int e = 0; e < 2; ++e) { const int j = 2 * jj + e; const float c = cs[2 * e], sn = cs[2 * e + 1];
;               const float x1 = qf[4 * h + a][j], x2 = qf[4 * h + 2 + a][j];
;               qf[4 * h + a][j] = x1 * c - x2 * sn; qf[4 * h + 2 + a][j] = x2 * c + x1 * sn; } } } }
	v_pk_mul_f32 v[120:121], v[120:121], v[166:167]
	v_pk_mul_f32 v[166:167], v[224:225], v[168:169] op_sel_hi:[0,1]
	s_waitcnt vmcnt(30)
	v_pk_mul_f32 v[116:117], v[116:117], v[166:167]
	v_pk_mul_f32 v[166:167], v[224:225], v[220:221] op_sel_hi:[0,1]
	v_pk_mul_f32 v[122:123], v[122:123], v[166:167]
	v_pk_mul_f32 v[166:167], v[224:225], v[216:217] op_sel_hi:[0,1]
	v_pk_mul_f32 v[118:119], v[118:119], v[166:167]
	v_pk_mul_f32 v[166:167], v[224:225], v[170:171] op_sel_hi:[0,1]
	s_waitcnt vmcnt(29)
	v_pk_mul_f32 v[112:113], v[112:113], v[166:167]
	v_pk_mul_f32 v[166:167], v[224:225], v[172:173] op_sel_hi:[0,1]
	s_waitcnt vmcnt(28)
	v_pk_mul_f32 v[108:109], v[108:109], v[166:167]
	v_pk_mul_f32 v[166:167], v[224:225], v[212:213] op_sel_hi:[0,1]
	v_pk_mul_f32 v[114:115], v[114:115], v[166:167]
	v_pk_mul_f32 v[166:167], v[224:225], v[190:191] op_sel_hi:[0,1]
	v_pk_mul_f32 v[110:111], v[110:111], v[166:167]
	v_pk_mul_f32 v[166:167], v[224:225], v[174:175] op_sel_hi:[0,1]
	s_waitcnt vmcnt(27)
	v_pk_mul_f32 v[166:167], v[104:105], v[166:167]
	v_pk_mul_f32 v[104:105], v[224:225], v[176:177] op_sel_hi:[0,1]
	s_waitcnt vmcnt(26)
	v_pk_mul_f32 v[168:169], v[100:101], v[104:105]
	v_pk_mul_f32 v[100:101], v[224:225], v[222:223] op_sel_hi:[0,1]
	v_pk_mul_f32 v[106:107], v[106:107], v[100:101]
	v_pk_mul_f32 v[100:101], v[224:225], v[218:219] op_sel_hi:[0,1]
	v_pk_mul_f32 v[170:171], v[102:103], v[100:101]
	v_pk_mul_f32 v[100:101], v[224:225], v[206:207] op_sel_hi:[0,1]
	s_waitcnt vmcnt(25)
	v_pk_mul_f32 v[96:97], v[96:97], v[100:101]
	v_pk_mul_f32 v[100:101], v[224:225], v[208:209] op_sel_hi:[0,1]
	s_waitcnt vmcnt(24)
	v_pk_mul_f32 v[172:173], v[92:93], v[100:101]
	v_pk_mul_f32 v[92:93], v[224:225], v[214:215] op_sel_hi:[0,1]
	v_pk_mul_f32 v[174:175], v[98:99], v[92:93]
	v_pk_mul_f32 v[92:93], v[224:225], v[210:211] op_sel_hi:[0,1]
	v_pk_mul_f32 v[176:177], v[94:95], v[92:93]
	v_pk_mul_f32 v[92:93], v[224:225], v[160:161] op_sel_hi:[0,1]
	s_waitcnt vmcnt(23)
	v_pk_mul_f32 v[160:161], v[88:89], v[92:93]
	v_pk_mul_f32 v[88:89], v[224:225], v[154:155] op_sel_hi:[0,1]
	s_waitcnt vmcnt(22)
	v_pk_mul_f32 v[102:103], v[84:85], v[88:89]
	v_pk_mul_f32 v[84:85], v[224:225], v[156:157] op_sel_hi:[0,1]
	v_pk_mul_f32 v[104:105], v[90:91], v[84:85]
	v_pk_mul_f32 v[84:85], v[224:225], v[148:149] op_sel_hi:[0,1]
	v_pk_mul_f32 v[100:101], v[86:87], v[84:85]
	v_pk_mul_f32 v[84:85], v[224:225], v[146:147] op_sel_hi:[0,1]
	s_waitcnt vmcnt(21)
	v_pk_mul_f32 v[98:99], v[84:85], v[80:81]
	v_pk_mul_f32 v[80:81], v[224:225], v[138:139] op_sel_hi:[0,1]
	s_waitcnt vmcnt(20)
	v_pk_mul_f32 v[80:81], v[80:81], v[76:77]
	v_pk_mul_f32 v[76:77], v[224:225], v[140:141] op_sel_hi:[0,1]
	v_pk_mul_f32 v[86:87], v[76:77], v[82:83]
	v_pk_mul_f32 v[76:77], v[224:225], v[132:133] op_sel_hi:[0,1]
	v_pk_mul_f32 v[76:77], v[76:77], v[78:79]
	v_pk_mul_f32 v[78:79], v[224:225], v[158:159] op_sel_hi:[0,1]
	s_waitcnt vmcnt(19)
	v_pk_mul_f32 v[132:133], v[78:79], v[68:69]
	v_pk_mul_f32 v[68:69], v[224:225], v[150:151] op_sel_hi:[0,1]
	s_waitcnt vmcnt(18)
	v_pk_mul_f32 v[64:65], v[68:69], v[64:65]
	v_pk_mul_f32 v[68:69], v[224:225], v[152:153] op_sel_hi:[0,1]
	v_pk_mul_f32 v[138:139], v[68:69], v[70:71]
	v_pk_mul_f32 v[68:69], v[224:225], v[144:145] op_sel_hi:[0,1]
	v_pk_mul_f32 v[66:67], v[68:69], v[66:67]
	v_pk_mul_f32 v[68:69], v[224:225], v[142:143] op_sel_hi:[0,1]
	s_waitcnt vmcnt(17)
	v_pk_mul_f32 v[60:61], v[68:69], v[60:61]
	v_pk_mul_f32 v[68:69], v[224:225], v[134:135] op_sel_hi:[0,1]
	s_waitcnt vmcnt(16)
	v_pk_mul_f32 v[78:79], v[68:69], v[52:53]
	v_pk_mul_f32 v[52:53], v[224:225], v[136:137] op_sel_hi:[0,1]
	v_pk_mul_f32 v[90:91], v[52:53], v[62:63]
	v_pk_mul_f32 v[46:47], v[224:225], v[46:47] op_sel_hi:[0,1]
	s_waitcnt vmcnt(12)
	v_mov_b32_e32 v53, v74
	v_mov_b32_e32 v74, v73
	v_pk_mul_f32 v[70:71], v[46:47], v[54:55]
	v_mov_b32_e32 v52, v72
	v_pk_mul_f32 v[46:47], v[166:167], v[74:75]
	v_ashrrev_i32_e32 v68, 4, v188
	v_pk_fma_f32 v[46:47], v[120:121], v[52:53], v[46:47] neg_lo:[0,0,1] neg_hi:[0,0,1]
	v_pk_mul_f32 v[52:53], v[166:167], v[52:53]
	v_add_u32_e32 v69, 32, v68
	v_pk_fma_f32 v[72:73], v[120:121], v[74:75], v[52:53]
	v_mov_b32_e32 v53, v58
	v_mov_b32_e32 v58, v57
	v_mov_b32_e32 v52, v56
	v_pk_mul_f32 v[54:55], v[106:107], v[58:59]
	v_lshlrev_b32_e32 v56, 3, v188
	v_pk_fma_f32 v[94:95], v[122:123], v[52:53], v[54:55] neg_lo:[0,0,1] neg_hi:[0,0,1]
	v_pk_mul_f32 v[52:53], v[106:107], v[52:53]
	v_and_b32_e32 v144, 0x78, v56
	v_pk_fma_f32 v[74:75], v[122:123], v[58:59], v[52:53]
	v_mov_b32_e32 v53, v40
	v_mov_b32_e32 v40, v39
	v_mov_b32_e32 v52, v38
	v_pk_mul_f32 v[38:39], v[168:169], v[40:41]
	v_lshlrev_b32_e32 v145, 4, v188
	v_pk_fma_f32 v[38:39], v[116:117], v[52:53], v[38:39] neg_lo:[0,0,1] neg_hi:[0,0,1]
	v_pk_mul_f32 v[52:53], v[168:169], v[52:53]
	v_lshlrev_b32_e32 v148, 8, v189
	v_pk_fma_f32 v[82:83], v[116:117], v[40:41], v[52:53]
	v_mov_b32_e32 v53, v32
	v_mov_b32_e32 v32, v31
	v_mov_b32_e32 v52, v30
	v_pk_mul_f32 v[30:31], v[170:171], v[32:33]
	v_and_b32_e32 v149, 0xf0, v145
	v_pk_fma_f32 v[40:41], v[118:119], v[52:53], v[30:31] neg_lo:[0,0,1] neg_hi:[0,0,1]
	v_pk_mul_f32 v[30:31], v[170:171], v[52:53]
	v_bitop3_b32 v214, v0, v148, v149 bitop3:0xde
	v_pk_fma_f32 v[84:85], v[118:119], v[32:33], v[30:31]
	s_waitcnt vmcnt(8)
; __device__ __forceinline__ unsigned cvtpk(float lo, float hi) { f32x2 v = {lo, hi}; bf16v2 b = __builtin_convertvector(v, bf16v2); return __builtin_bit_cast(unsigned, b); }
; __device__ __forceinline__ int v_st(int k, int c) { const int kk = (k & ~0xC) | ((k & 4) << 1) | ((k & 8) >> 1); return ((kk >> 3) * 4 + (c >> 5)) * 512 + ((kk & 7) * 32 + (c & 31)) * 2; }
; __device__ __forceinline__ int v_rd_base(int lane) { return ((lane & 3) << 3) | (((lane >> 2) & 3) << 6) | (((lane >> 4) & 1) << 5) | (((lane >> 5) & 1) << 8); }
; #define SLOAD(i, k0) do { sr_[i].vs0 = *reinterpret_cast<const bf16x8*>(&Vh[(size_t)((k0) + sr) * LDQK + sc]); sr_[i].vs1 = *reinterpret_cast<const bf16x8*>(&Vh[(size_t)((k0) + 32 + sr) * LDQK + sc]); \
;     sr_[i].ks0 = *reinterpret_cast<const bf16x8*>(&Kh[(size_t)((k0) + sr) * LDQK + sc]); sr_[i].ks1 = *reinterpret_cast<const bf16x8*>(&Kh[(size_t)((k0) + 32 + sr) * LDQK + sc]); } while (0)
; template <int MODE>
; __device__ __forceinline__ void attn_body(const bf16_t* __restrict__ Qb, const bf16_t* __restrict__ Kh, const bf16_t* __restrict__ Vh, int NT, int krel0,
;                                           char* lds, const float* __restrict__ lutg, const AttnEpi& E) {
;     ...
; #pragma unroll
;             for (int e = 0; e < 2; ++e) { const int j = 2 * jj + e; const float c = cs[2 * e], sn = cs[2 * e + 1];
;               const float x1 = qf[4 * h + a][j], x2 = qf[4 * h + 2 + a][j];
;               qf[4 * h + a][j] = x1 * c - x2 * sn; qf[4 * h + 2 + a][j] = x2 * c + x1 * sn; } } } }
;     }
; #pragma unroll
;     for (int d0 = 0; d0 < ND0; ++d0) { u32x4 w; w.x = cvtpk(qf[d0][0], qf[d0][1]); w.y = cvtpk(qf[d0][2], qf[d0][3]); w.z = cvtpk(qf[d0][4], qf[d0][5]); w.w = cvtpk(qf[d0][6], qf[d0][7]);
;       qr[d0] = *reinterpret_cast<bf16x8*>(&w); }
;   }
;   const int sr = tid >> 4, sc = (tid & 15) * 8, vst0 = v_st(sr, sc), vst1 = v_st(32 + sr, sc);
;   const int vb0 = (int)(uintptr_t)V_lds + v_rd_base(lane);
;   struct { bf16x8 vs0, vs1, ks0, ks1; } sr_[2];
;     ...
;   const int relq = krel0 - (wid * 32 + r32) + 4 * hi, relwmin = krel0 - (wid * 32 + 31), relwmax = krel0 + 63 - wid * 32;
;     ...
;   f32x16 pA0, pA1, pB0, pB1; float mnA, mnB, alA, alB; bf16x8 pa0, pa1, pa2, pa3;
;   constexpr int SE = 0, SO = 1;
;   SLOAD(SE, 0); SLOAD(SO, 64); asm volatile("s_waitcnt vmcnt(4)" ::: "memory"); SWRITE(0, SE); __syncthreads();
	v_mov_b32_e32 v31, v44
	v_mov_b32_e32 v44, v43
	v_mov_b32_e32 v30, v42
	v_pk_mul_f32 v[32:33], v[96:97], v[44:45]
	v_mad_i64_i32 v[42:43], s[6:7], v69, s57, 0
	v_pk_fma_f32 v[88:89], v[112:113], v[30:31], v[32:33] neg_lo:[0,0,1] neg_hi:[0,0,1]
	v_mov_b32_e32 v33, v36
	v_mov_b32_e32 v36, v35
	v_mov_b32_e32 v32, v34
	v_pk_mul_f32 v[34:35], v[174:175], v[36:37]
	v_pk_mul_f32 v[30:31], v[96:97], v[30:31]
	v_pk_fma_f32 v[92:93], v[114:115], v[32:33], v[34:35] neg_lo:[0,0,1] neg_hi:[0,0,1]
	v_mov_b32_e32 v35, v28
	v_mov_b32_e32 v28, v27
	v_mov_b32_e32 v34, v26
	v_pk_mul_f32 v[26:27], v[172:173], v[28:29]
	v_or_b32_e32 v42, v42, v144
	v_pk_fma_f32 v[96:97], v[108:109], v[34:35], v[26:27] neg_lo:[0,0,1] neg_hi:[0,0,1]
	v_pk_mul_f32 v[26:27], v[172:173], v[34:35]
	v_mov_b32_e32 v35, v20
	v_mov_b32_e32 v20, v19
	v_mov_b32_e32 v34, v18
	v_pk_mul_f32 v[18:19], v[176:177], v[20:21]
	v_pk_fma_f32 v[26:27], v[108:109], v[28:29], v[26:27]
	v_pk_fma_f32 v[28:29], v[110:111], v[34:35], v[18:19] neg_lo:[0,0,1] neg_hi:[0,0,1]
	v_pk_mul_f32 v[18:19], v[176:177], v[34:35]
	v_pk_mul_f32 v[32:33], v[174:175], v[32:33]
	v_pk_fma_f32 v[18:19], v[110:111], v[20:21], v[18:19]
	s_waitcnt vmcnt(4)
	v_mov_b32_e32 v20, v14
	v_mov_b32_e32 v21, v16
	v_mov_b32_e32 v16, v15
	v_mad_i64_i32 v[14:15], s[6:7], v68, s57, 0
	v_or_b32_e32 v14, v14, v144
	v_pk_mul_f32 v[54:55], v[132:133], v[16:17]
	v_lshl_add_u64 v[14:15], v[14:15], 1, s[0:1]
	v_lshl_add_u64 v[52:53], v[42:43], 1, s[0:1]
	v_pk_fma_f32 v[110:111], v[160:161], v[20:21], v[54:55] neg_lo:[0,0,1] neg_hi:[0,0,1]
	v_pk_mul_f32 v[20:21], v[132:133], v[20:21]
	v_pk_fma_f32 v[30:31], v[112:113], v[44:45], v[30:31]
	v_pk_fma_f32 v[32:33], v[114:115], v[36:37], v[32:33]
	global_load_dwordx4 v[34:37], v[14:15], off offset:2560
	global_load_dwordx4 v[42:45], v[52:53], off offset:2560
	v_pk_fma_f32 v[132:133], v[160:161], v[16:17], v[20:21]
	global_load_dwordx4 v[14:17], v[14:15], off offset:2048
	v_mov_b32_e32 v21, v12
	global_load_dwordx4 v[106:109], v[52:53], off offset:2048
	v_mov_b32_e32 v12, v11
	v_mov_b32_e32 v20, v10
	v_pk_mul_f32 v[10:11], v[138:139], v[12:13]
	v_cvt_pk_bf16_f32 v116, v38, v39
	v_pk_fma_f32 v[112:113], v[104:105], v[20:21], v[10:11] neg_lo:[0,0,1] neg_hi:[0,0,1]
	v_pk_mul_f32 v[10:11], v[138:139], v[20:21]
	v_or_b32_e32 v38, 32, v0
	v_pk_fma_f32 v[104:105], v[104:105], v[12:13], v[10:11]
	v_mov_b32_e32 v11, v8
	v_mov_b32_e32 v8, v7
	v_mov_b32_e32 v10, v6
	v_pk_mul_f32 v[6:7], v[64:65], v[8:9]
	s_waitcnt vmcnt(6)
	v_mov_b32_e32 v21, v50
	v_pk_fma_f32 v[134:135], v[102:103], v[10:11], v[6:7] neg_lo:[0,0,1] neg_hi:[0,0,1]
	v_pk_mul_f32 v[6:7], v[64:65], v[10:11]
	v_mov_b32_e32 v50, v49
	v_pk_fma_f32 v[136:137], v[102:103], v[8:9], v[6:7]
	v_mov_b32_e32 v7, v4
	v_mov_b32_e32 v4, v3
	v_mov_b32_e32 v6, v2
	v_pk_mul_f32 v[2:3], v[66:67], v[4:5]
	v_lshlrev_b32_e32 v8, 1, v144
	v_pk_fma_f32 v[102:103], v[100:101], v[6:7], v[2:3] neg_lo:[0,0,1] neg_hi:[0,0,1]
	v_pk_mul_f32 v[2:3], v[66:67], v[6:7]
	s_waitcnt vmcnt(5)
	v_mov_b32_e32 v7, v126
	v_pk_fma_f32 v[138:139], v[100:101], v[4:5], v[2:3]
	s_waitcnt vmcnt(4)
	v_mov_b32_e32 v3, v130
	v_mov_b32_e32 v130, v129
	v_mov_b32_e32 v2, v128
	v_pk_mul_f32 v[4:5], v[60:61], v[130:131]
	v_mov_b32_e32 v126, v125
	v_pk_fma_f32 v[140:141], v[98:99], v[2:3], v[4:5] neg_lo:[0,0,1] neg_hi:[0,0,1]
	v_pk_mul_f32 v[2:3], v[60:61], v[2:3]
	v_mov_b32_e32 v6, v124
	v_pk_fma_f32 v[130:131], v[98:99], v[130:131], v[2:3]
	v_pk_mul_f32 v[2:3], v[90:91], v[126:127]
	v_bfe_u32 v4, v56, 5, 2
	v_pk_fma_f32 v[142:143], v[86:87], v[6:7], v[2:3] neg_lo:[0,0,1] neg_hi:[0,0,1]
	v_and_b32_e32 v2, 0xfffff0, v68
	v_lshlrev_b32_e32 v3, 1, v68
	v_and_or_b32 v2, v3, 8, v2
	v_lshrrev_b32_e32 v3, 1, v68
	v_lshrrev_b32_e32 v2, 1, v2
	v_and_b32_e32 v5, 3, v68
	v_or_b32_e32 v2, v2, v4
	v_and_or_b32 v3, v3, 4, v5
	v_lshlrev_b32_e32 v2, 9, v2
	v_lshlrev_b32_e32 v3, 6, v3
	v_and_b32_e32 v5, 48, v8
	v_or3_b32 v210, v2, v3, v5
	v_and_b32_e32 v2, 0xfffff0, v69
	v_lshlrev_b32_e32 v9, 1, v69
	v_and_or_b32 v2, v9, 8, v2
	v_lshrrev_b32_e32 v2, 1, v2
	v_or_b32_e32 v2, v2, v4
	v_lshlrev_b32_e32 v2, 9, v2
	v_or3_b32 v211, v2, v3, v5
	v_add_u32_e32 v2, 64, v68
	v_mad_i64_i32 v[2:3], s[6:7], v2, s57, 0
	v_add_u32_e32 v4, 0x60, v68
	v_or_b32_e32 v2, v2, v144
	v_mad_i64_i32 v[4:5], s[6:7], v4, s57, 0
	v_lshl_add_u64 v[2:3], v[2:3], 1, s[0:1]
	v_or_b32_e32 v4, v4, v144
	v_lshl_add_u64 v[4:5], v[4:5], 1, s[0:1]
	global_load_dwordx4 v[60:63], v[2:3], off offset:2560
	global_load_dwordx4 v[52:55], v[2:3], off offset:2048
	global_load_dwordx4 v[64:67], v[4:5], off offset:2560
	global_load_dwordx4 v[56:59], v[4:5], off offset:2048
	v_lshlrev_b32_e32 v2, 8, v68
	v_and_b32_e32 v3, 0xf0, v188
	v_bitop3_b32 v212, v8, v2, v3 bitop3:0xde
	v_add_u32_e32 v146, 0, v210
	v_add_u32_e32 v147, 0, v211
	v_add_u32_e32 v2, 0, v212
	s_waitcnt vmcnt(4)
	s_waitcnt vmcnt(7)
	ds_write_b128 v146, v[34:37]
	s_waitcnt vmcnt(6)
	ds_write_b128 v147, v[42:45]
	s_waitcnt vmcnt(5)
	ds_write_b128 v2, v[14:17] offset:49152
	v_lshlrev_b32_e32 v2, 8, v69
	v_bitop3_b32 v213, v8, v2, v3 bitop3:0xde
	v_add_u32_e32 v2, 0, v213
	v_add_u32_e32 v8, 0, v214
	s_waitcnt vmcnt(4)
	ds_write_b128 v2, v[106:109] offset:49152
	s_waitcnt lgkmcnt(0)
	s_barrier
; template <int MODE>
; __device__ __forceinline__ void partialSM(f32x16& p0, f32x16& p1, float& m_reg, float& mn, float& alpha, int relh, int relw_min, int relw_max, const float* lut) {
;     ...
;     float pmax = p0[0];
; #pragma unroll
;     for (int r = 1; r < 16; ++r) pmax = fmaxf(pmax, p0[r]);
; #pragma unroll
;     for (int r = 0; r < 16; ++r) pmax = fmaxf(pmax, p1[r]);
; template <int ND0, int DOFF>
; __device__ __forceinline__ void qkt(f32x16& p0, f32x16& p1, const char* Ks, const bf16x8* qr, int r32, int hi) {
;   p0 = f32x16{}; p1 = f32x16{};
; #pragma unroll
;   for (int d0 = 0; d0 < ND0; ++d0) { const int cb = ((d0 + DOFF) * 16 + hi * 8) * 2;
;     bf16x8 b0 = *reinterpret_cast<const bf16x8*>(Ks + KSWZ(r32, cb));
;     bf16x8 b1 = *reinterpret_cast<const bf16x8*>(Ks + KSWZ(32 + r32, cb));
;     p0 = __builtin_amdgcn_mfma_f32_32x32x16_bf16(b0, qr[d0], p0, 0, 0, 0);
;     p1 = __builtin_amdgcn_mfma_f32_32x32x16_bf16(b1, qr[d0], p1, 0, 0, 0); }
; }
	ds_read_b128 v[2:5], v8 offset:49152
	ds_read_b128 v[34:37], v8 offset:57344
	v_pk_mul_f32 v[6:7], v[90:91], v[6:7]
	v_bitop3_b32 v218, v38, v148, v149 bitop3:0xde
	v_pk_fma_f32 v[90:91], v[86:87], v[126:127], v[6:7]
	v_mov_b32_e32 v20, v48
	v_pk_mul_f32 v[86:87], v[78:79], v[50:51]
	v_add_u32_e32 v69, 0, v218
	v_cvt_pk_bf16_f32 v114, v46, v47
	v_cvt_pk_bf16_f32 v115, v94, v95
	v_cvt_pk_bf16_f32 v117, v40, v41
	v_pk_fma_f32 v[94:95], v[80:81], v[20:21], v[86:87] neg_lo:[0,0,1] neg_hi:[0,0,1]
	v_cvt_pk_bf16_f32 v126, v88, v89
	ds_read_b128 v[86:89], v69 offset:57344
	s_waitcnt lgkmcnt(1)
	v_mfma_f32_32x32x16_bf16 v[34:49], v[34:37], v[114:117], 0
	ds_read_b128 v[98:101], v69 offset:49152
	v_mul_f32_e64 v20, v78, v20
	v_mul_f32_e64 v21, v79, v21
	v_cvt_pk_bf16_f32 v127, v92, v93
	v_cvt_pk_bf16_f32 v128, v96, v97
	v_cvt_pk_bf16_f32 v129, v28, v29
	v_pk_fma_f32 v[28:29], v[80:81], v[50:51], v[20:21]
	v_mov_b32_e32 v51, v24
	v_mfma_f32_32x32x16_bf16 v[2:17], v[2:5], v[114:117], 0
	v_mov_b32_e32 v24, v23
	v_mov_b32_e32 v50, v22
	v_or_b32_e32 v20, 64, v0
	v_cvt_pk_bf16_f32 v119, v74, v75
	v_bitop3_b32 v219, v20, v148, v149 bitop3:0xde
	v_add_u32_e32 v20, 0, v219
	ds_read_b128 v[78:81], v20 offset:49152
	s_waitcnt lgkmcnt(2)
	v_mfma_f32_32x32x16_bf16 v[34:49], v[86:89], v[126:129], v[34:49]
	v_mul_f32_e64 v86, v70, v24
	v_mul_f32_e64 v87, v71, v25
	v_cvt_pk_bf16_f32 v118, v72, v73
	v_fma_f32 v74, v76, v50, -v86
	v_fma_f32 v75, v77, v51, -v87
	v_pk_mul_f32 v[50:51], v[70:71], v[50:51]
	v_cvt_pk_bf16_f32 v120, v82, v83
	v_pk_fma_f32 v[50:51], v[76:77], v[24:25], v[50:51]
	v_or_b32_e32 v24, 0x60, v0
	v_bitop3_b32 v216, v24, v148, v149 bitop3:0xde
	v_add_u32_e32 v24, 0, v216
	ds_read_b128 v[70:73], v24 offset:49152
	ds_read_b128 v[20:23], v20 offset:57344
	s_waitcnt lgkmcnt(3)
	v_mfma_f32_32x32x16_bf16 v[2:17], v[98:101], v[126:129], v[2:17]
	v_cvt_pk_bf16_f32 v121, v84, v85
	v_cvt_pk_bf16_f32 v124, v26, v27
	v_cvt_pk_bf16_f32 v122, v30, v31
	v_cvt_pk_bf16_f32 v123, v32, v33
	v_cvt_pk_bf16_f32 v125, v18, v19
	v_cvt_pk_bf16_f32 v110, v110, v111
	v_cvt_pk_bf16_f32 v111, v112, v113
	s_waitcnt lgkmcnt(2)
	v_mfma_f32_32x32x16_bf16 v[2:17], v[78:81], v[118:121], v[2:17]
	v_cvt_pk_bf16_f32 v112, v134, v135
	v_cvt_pk_bf16_f32 v113, v102, v103
	v_cvt_pk_bf16_f32 v106, v140, v141
	v_cvt_pk_bf16_f32 v107, v142, v143
	v_cvt_pk_bf16_f32 v108, v94, v95
	v_cvt_pk_bf16_f32 v109, v74, v75
	v_cvt_pk_bf16_f32 v100, v28, v29
	s_waitcnt lgkmcnt(0)
	v_mfma_f32_32x32x16_bf16 v[34:49], v[20:23], v[118:121], v[34:49]
	v_or_b32_e32 v22, 0x80, v0
	v_bitop3_b32 v217, v22, v148, v149 bitop3:0xde
	v_add_u32_e32 v26, 0, v217
	ds_read_b128 v[18:21], v24 offset:57344
	ds_read_b128 v[22:25], v26 offset:49152
	v_lshlrev_b32_e32 v27, 3, v162
	v_lshlrev_b32_e32 v29, 1, v188
	v_mfma_f32_32x32x16_bf16 v[2:17], v[70:73], v[122:125], v[2:17]
	v_cvt_pk_bf16_f32 v102, v132, v133
	v_cvt_pk_bf16_f32 v103, v104, v105
	v_cvt_pk_bf16_f32 v104, v136, v137
	v_cvt_pk_bf16_f32 v105, v138, v139
	s_cselect_b32 s6, 0, 0
	v_cvt_pk_bf16_f32 v98, v130, v131
	v_cvt_pk_bf16_f32 v99, v90, v91
	s_waitcnt lgkmcnt(1)
	v_mfma_f32_32x32x16_bf16 v[34:49], v[18:21], v[122:125], v[34:49]
	ds_read_b128 v[18:21], v26 offset:57344
	v_cvt_pk_bf16_f32 v101, v50, v51
	v_lshlrev_b32_e32 v205, 2, v164
	v_ashrrev_i32_e32 v69, 31, v68
	v_lshl_add_u32 v206, v189, 2, v163
	v_mov_b32_e32 v207, 0
	s_waitcnt lgkmcnt(1)
	v_mfma_f32_32x32x16_bf16 v[2:17], v[22:25], v[110:113], v[2:17]
	v_or_b32_e32 v22, 0xa0, v0
	v_bitop3_b32 v215, v22, v148, v149 bitop3:0xde
	v_add_u32_e32 v26, 0, v215
	ds_read_b128 v[22:25], v26 offset:49152
	s_waitcnt lgkmcnt(1)
	v_mfma_f32_32x32x16_bf16 v[34:49], v[18:21], v[110:113], v[34:49]
	v_and_b32_e32 v18, 0xc0, v145
	v_and_or_b32 v28, v27, 24, v18
	ds_read_b128 v[18:21], v26 offset:57344
	s_waitcnt lgkmcnt(1)
	v_mfma_f32_32x32x16_bf16 v[2:17], v[22:25], v[106:109], v[2:17]
	v_and_b32_e32 v22, 32, v29
	v_and_b32_e32 v23, 0x100, v27
	v_or3_b32 v26, v28, v22, v23
	v_or_b32_e32 v22, 0xc0, v0
	v_bitop3_b32 v220, v22, v148, v149 bitop3:0xde
	v_add_u32_e32 v27, 0, v220
	ds_read_b128 v[22:25], v27 offset:49152
	s_waitcnt lgkmcnt(1)
	v_mfma_f32_32x32x16_bf16 v[34:49], v[18:21], v[106:109], v[34:49]
	ds_read_b128 v[18:21], v27 offset:57344
	v_add_u32_e32 v209, s6, v26
	s_waitcnt lgkmcnt(1)
	v_mfma_f32_32x32x16_bf16 v[2:17], v[22:25], v[102:105], v[2:17]
	v_or_b32_e32 v22, 0xe0, v0
	v_bitop3_b32 v221, v22, v148, v149 bitop3:0xde
	v_add_u32_e32 v26, 0, v221
	ds_read_b128 v[22:25], v26 offset:49152
	ds_read_b128 v[70:73], v26 offset:57344
	v_add_u32_e32 v0, v163, v0
	s_waitcnt lgkmcnt(1)
	v_mfma_f32_32x32x16_bf16 v[2:17], v[22:25], v[98:101], v[2:17]
	v_mfma_f32_32x32x16_bf16 v[34:49], v[18:21], v[102:105], v[34:49]
	s_nop 10
	v_max_f32_e32 v50, v3, v3
	v_max_f32_e32 v51, v2, v2
	v_max_f32_e32 v50, v51, v50
	v_max3_f32 v50, v50, v4, v5
	v_max3_f32 v50, v50, v6, v7
	v_max3_f32 v50, v50, v8, v9
	v_max3_f32 v50, v50, v10, v11
	s_waitcnt lgkmcnt(0)
; #define SLOAD(i, k0) do { sr_[i].vs0 = *reinterpret_cast<const bf16x8*>(&Vh[(size_t)((k0) + sr) * LDQK + sc]); sr_[i].vs1 = *reinterpret_cast<const bf16x8*>(&Vh[(size_t)((k0) + 32 + sr) * LDQK + sc]); \
;     sr_[i].ks0 = *reinterpret_cast<const bf16x8*>(&Kh[(size_t)((k0) + sr) * LDQK + sc]); sr_[i].ks1 = *reinterpret_cast<const bf16x8*>(&Kh[(size_t)((k0) + 32 + sr) * LDQK + sc]); } while (0)
; #define SWRITE(off, i) do { *(bf16x8*)(V_lds + (off) + vst0) = sr_[i].vs0;          \
;     *(bf16x8*)(V_lds + (off) + vst1) = sr_[i].vs1; int kc = sc * 2;               \
;     *(bf16x8*)(K_lds + (off) + KSWZ(sr, kc)) = sr_[i].ks0;                       \
;     *(bf16x8*)(K_lds + (off) + KSWZ(32 + sr, kc)) = sr_[i].ks1; } while (0)
; #define SWAIT() asm volatile("s_waitcnt vmcnt(4)" ::: "memory")
; #define PSM(P0, P1, MN, AL, J) partialSM<MODE>(P0, P1, m_reg, MN, AL, relq + 64 * (J), relwmin + 64 * (J), relwmax + 64 * (J), lut)
; template <int MODE>
; __device__ __forceinline__ void partialSM(f32x16& p0, f32x16& p1, float& m_reg, float& mn, float& alpha, int relh, int relw_min, int relw_max, const float* lut) {
;     ...
;     for (int r = 0; r < 16; ++r) pmax = fmaxf(pmax, p1[r]);
;     { auto rr = __builtin_amdgcn_permlane32_swap(__float_as_uint(pmax), __float_as_uint(pmax), false, false);
;       pmax = fmaxf(__uint_as_float(rr[0]), __uint_as_float(rr[1])); }
;     if (__builtin_expect(__all(pmax - m_reg <= THR / SCALE), 1)) { mn = m_reg; alpha = 1.f; }
;     else { mn = fmaxf(m_reg, pmax); alpha = __builtin_amdgcn_exp2f((m_reg - mn) * C); m_reg = mn; }
;     const float mnC = -mn * C;
; #pragma unroll
;     for (int r = 0; r < 16; ++r) p0[r] = fmaf(p0[r], C, mnC);
; #pragma unroll
;     for (int r = 0; r < 16; ++r) p1[r] = fmaf(p1[r], C, mnC);
; #pragma unroll
;     for (int r = 0; r < 16; ++r) p0[r] = __builtin_amdgcn_exp2f(p0[r]);
; template <int MODE>
; __device__ __forceinline__ void attn_body(const bf16_t* __restrict__ Qb, const bf16_t* __restrict__ Kh, const bf16_t* __restrict__ Vh, int NT, int krel0,
;                                           char* lds, const float* __restrict__ lutg, const AttnEpi& E) {
;     ...
;   SLOAD(SE, 0); SLOAD(SO, 64); asm volatile("s_waitcnt vmcnt(4)" ::: "memory"); SWRITE(0, SE); __syncthreads();
;   qkt<ND0, DOFF>(pA0, pA1, K_lds, qr, r32, hi); PSM(pA0, pA1, mnA, alA, 0);
;   if (2 < NT) SLOAD(SE, 2 * 64);
;   SWAIT(); SWRITE(SHM_V, SO);
	v_mfma_f32_32x32x16_bf16 v[34:49], v[70:73], v[98:101], v[34:49]
	v_max3_f32 v50, v50, v12, v13
	v_max3_f32 v50, v50, v14, v15
	v_max3_f32 v50, v50, v16, v17
	v_add_u32_e32 v70, 0x80, v68
	v_mad_i64_i32 v[70:71], s[6:7], v70, s57, 0
	v_or_b32_e32 v70, v70, v144
	s_nop 5
	v_max3_f32 v50, v50, v34, v35
	v_max3_f32 v50, v50, v36, v37
	v_max3_f32 v50, v50, v38, v39
	v_max3_f32 v50, v50, v40, v41
	v_max3_f32 v50, v50, v42, v43
	v_max3_f32 v50, v50, v44, v45
	v_max3_f32 v50, v50, v46, v47
	v_max3_f32 v72, v50, v48, v49
	v_mov_b32_e32 v50, v72
	s_nop 1
	v_permlane32_swap_b32_e32 v72, v50
	v_max_f32_e32 v73, v50, v50
	v_add_u32_e32 v50, 0xa0, v68
	v_mad_i64_i32 v[50:51], s[6:7], v50, s57, 0
	v_or_b32_e32 v50, v50, v144
	v_lshl_add_u64 v[50:51], v[50:51], 1, s[0:1]
	v_lshl_add_u64 v[70:71], v[70:71], 1, s[0:1]
	global_load_dwordx4 v[134:137], v[50:51], off offset:2048
	global_load_dwordx4 v[138:141], v[50:51], off offset:2560
	global_load_dwordx4 v[142:145], v[70:71], off offset:2048
	global_load_dwordx4 v[130:133], v[70:71], off offset:2560
	v_max_f32_e32 v50, v72, v72
	v_max_f32_e32 v50, v50, v73
	v_mov_b64_e32 v[18:19], s[68:69]
	v_add_f32_e32 v51, 0x7149f2ca, v50
	v_mov_b64_e32 v[20:21], s[70:71]
	v_mov_b64_e32 v[22:23], s[72:73]
	v_mov_b64_e32 v[24:25], s[74:75]
	v_mov_b64_e32 v[26:27], s[76:77]
	v_mov_b64_e32 v[28:29], s[78:79]
	v_mov_b64_e32 v[30:31], s[80:81]
	v_mov_b64_e32 v[32:33], s[82:83]
	v_cmp_ge_f32_e32 vcc, s40, v51
	s_add_i32 s75, 0, 0x10000
	s_add_i32 s70, s11, -1
	s_cmp_eq_u64 vcc, exec
	v_add_u32_e32 v51, s75, v212
	v_max_f32_e32 v50, 0xf149f2ca, v50
	s_cselect_b64 vcc, -1, 0
	s_waitcnt vmcnt(4)
	s_waitcnt vmcnt(7)
	ds_write_b128 v146, v[60:63] offset:16384
	s_waitcnt vmcnt(5)
	ds_write_b128 v147, v[64:67] offset:16384
	ds_write_b128 v51, v[52:55]
	v_add_u32_e32 v51, s75, v213
	v_cndmask_b32_e32 v166, v50, v197, vcc
	v_readlane_b32 s19, v255, 20
	s_nop 3
	v_mov_b32_e32 v166, s19
	s_waitcnt vmcnt(4)
	ds_write_b128 v51, v[56:59]
	v_sub_f32_e32 v51, 0xf149f2ca, v50
	v_mul_f32_e32 v50, 0xbe0293ee, v166
	v_fmamk_f32 v2, v2, 0x3e0293ee, v50
	v_exp_f32_e32 v164, v2
	v_fmamk_f32 v2, v3, 0x3e0293ee, v50
	v_exp_f32_e32 v165, v2
	v_fmamk_f32 v2, v4, 0x3e0293ee, v50
	v_exp_f32_e32 v175, v2
	v_fmamk_f32 v2, v5, 0x3e0293ee, v50
	v_exp_f32_e32 v177, v2
	v_fmamk_f32 v2, v6, 0x3e0293ee, v50
	v_exp_f32_e32 v227, v2
	v_fmamk_f32 v2, v7, 0x3e0293ee, v50
	v_exp_f32_e32 v228, v2
	v_fmamk_f32 v2, v8, 0x3e0293ee, v50
	v_exp_f32_e32 v176, v2
	v_fmamk_f32 v2, v9, 0x3e0293ee, v50
	v_exp_f32_e32 v226, v2
	v_fmamk_f32 v2, v10, 0x3e0293ee, v50
	v_exp_f32_e32 v167, v2
	v_fmamk_f32 v2, v11, 0x3e0293ee, v50
	v_exp_f32_e32 v169, v2
	v_fmamk_f32 v2, v12, 0x3e0293ee, v50
	v_mul_f32_e32 v51, 0x3e0293ee, v51
	v_exp_f32_e32 v171, v2
	v_fmamk_f32 v2, v13, 0x3e0293ee, v50
	v_exp_f32_e32 v51, v51
	v_exp_f32_e32 v173, v2
	v_fmamk_f32 v2, v14, 0x3e0293ee, v50
	v_exp_f32_e32 v168, v2
	v_fmamk_f32 v2, v15, 0x3e0293ee, v50
	v_exp_f32_e32 v170, v2
	v_fmamk_f32 v2, v16, 0x3e0293ee, v50
	v_exp_f32_e32 v172, v2
	v_lshl_add_u64 v[2:3], v[68:69], 0, s[2:3]
	v_pk_fma_f32 v[146:147], v[48:49], s[38:39], v[50:51] op_sel_hi:[1,0,0]
	v_pk_fma_f32 v[148:149], v[46:47], s[38:39], v[50:51] op_sel_hi:[1,0,0]
	v_pk_fma_f32 v[150:151], v[44:45], s[38:39], v[50:51] op_sel_hi:[1,0,0]
	v_pk_fma_f32 v[152:153], v[42:43], s[38:39], v[50:51] op_sel_hi:[1,0,0]
	v_pk_fma_f32 v[154:155], v[40:41], s[38:39], v[50:51] op_sel_hi:[1,0,0]
	v_pk_fma_f32 v[156:157], v[38:39], s[38:39], v[50:51] op_sel_hi:[1,0,0]
	v_pk_fma_f32 v[158:159], v[36:37], s[38:39], v[50:51] op_sel_hi:[1,0,0]
	v_pk_fma_f32 v[160:161], v[34:35], s[38:39], v[50:51] op_sel_hi:[1,0,0]
	v_fmac_f32_e32 v50, 0x3e0293ee, v17
	v_mad_u64_u32 v[4:5], s[0:1], v2, s56, 0
	v_and_b32_e32 v2, 15, v188
	s_mov_b32 s82, s84
	v_exp_f32_e32 v174, v50
	v_lshlrev_b32_e32 v2, 4, v2
	v_readlane_b32 s0, v254, 10
	v_mad_i32_i24 v3, v3, s56, v5
	v_or3_b32 v2, v4, s82, v2
	v_readlane_b32 s1, v254, 11
	v_cndmask_b32_e64 v222, v51, 1.0, vcc
	v_mov_b64_e32 v[64:65], v[32:33]
	v_lshl_add_u64 v[190:191], s[0:1], 0, v[2:3]
	v_mov_b64_e32 v[48:49], v[32:33]
	v_mov_b64_e32 v[2:3], v[18:19]
	s_mov_b64 s[86:87], s[22:23]
	v_cmp_gt_u32_e64 s[6:7], 32, v162
	s_movk_i32 s73, 0x2400
	s_movk_i32 s71, 0x4000
	s_mov_b32 s0, 0x8000
	v_mov_b64_e32 v[62:63], v[30:31]
	v_mov_b64_e32 v[60:61], v[28:29]
	v_mov_b64_e32 v[58:59], v[26:27]
	v_mov_b64_e32 v[56:57], v[24:25]
	v_mov_b64_e32 v[54:55], v[22:23]
	v_mov_b64_e32 v[52:53], v[20:21]
	v_mov_b64_e32 v[50:51], v[18:19]
	v_mov_b64_e32 v[46:47], v[30:31]
	v_mov_b64_e32 v[44:45], v[28:29]
	v_mov_b64_e32 v[42:43], v[26:27]
	v_mov_b64_e32 v[40:41], v[24:25]
	v_mov_b64_e32 v[38:39], v[22:23]
	v_mov_b64_e32 v[36:37], v[20:21]
	v_mov_b64_e32 v[34:35], v[18:19]
	v_mov_b64_e32 v[4:5], v[20:21]
	v_mov_b64_e32 v[6:7], v[22:23]
	v_mov_b64_e32 v[8:9], v[24:25]
	v_mov_b64_e32 v[10:11], v[26:27]
	v_mov_b64_e32 v[12:13], v[28:29]
	v_mov_b64_e32 v[14:15], v[30:31]
	v_mov_b64_e32 v[16:17], v[32:33]
	s_mov_b64 s[84:85], s[20:21]
	v_readlane_b32 s74, v254, 57
	s_waitcnt vmcnt(0)
	v_readfirstlane_b32 s31, v179
	s_nop 3
	s_lshr_b32 s31, s31, 6
	s_lshl_b32 s30, s31, 11
	v_and_b32_e32 v134, 63, v179
	v_bfe_u32 v135, v134, 2, 3
	s_lshl_b32 s29, s31, 3
	v_or_b32_e32 v135, s29, v135
	v_and_b32_e32 v136, 4, v135
	v_lshlrev_b32_e32 v136, 1, v136
	v_and_b32_e32 v137, 8, v135
	v_lshrrev_b32_e32 v137, 1, v137
	v_and_b32_e32 v135, 0xfffffff3, v135
	v_or3_b32 v135, v135, v136, v137
	v_mul_u32_u24_e32 v135, 0x2400, v135
	v_lshrrev_b32_e32 v136, 5, v134
	v_lshlrev_b32_e32 v136, 6, v136
	v_and_b32_e32 v137, 3, v134
	v_lshlrev_b32_e32 v137, 4, v137
	v_add3_u32 v130, v135, v136, v137
	v_add_u32_e32 v131, 0x80, v130
	v_lshrrev_b32_e32 v135, 4, v134
	v_add_u32_e32 v135, s29, v135
	v_and_b32_e32 v136, 15, v134
	v_and_b32_e32 v137, 15, v135
	v_xor_b32_e32 v137, v136, v137
	v_mul_u32_u24_e32 v138, 0x2400, v135
	v_lshl_add_u32 v132, v137, 4, v138
	v_add_u32_e32 v135, 4, v135
	v_and_b32_e32 v137, 15, v135
	v_xor_b32_e32 v137, v136, v137
	v_mul_u32_u24_e32 v138, 0x2400, v135
	v_lshl_add_u32 v133, v137, 4, v138
	v_readfirstlane_b32 s26, v190
	v_readfirstlane_b32 s27, v191
	s_mul_i32 s29, s31, 0x9000
	s_add_u32 s29, s29, 0x168000
	s_sub_u32 s26, s26, s29
	s_subb_u32 s27, s27, 0
	s_sub_u32 s28, s26, 0x200
	s_subb_u32 s29, s27, 0
; #define SBAR() __builtin_amdgcn_sched_barrier(0)
; #define SLOAD(i, k0) do { sr_[i].vs0 = *reinterpret_cast<const bf16x8*>(&Vh[(size_t)((k0) + sr) * LDQK + sc]); sr_[i].vs1 = *reinterpret_cast<const bf16x8*>(&Vh[(size_t)((k0) + 32 + sr) * LDQK + sc]); \
;     sr_[i].ks0 = *reinterpret_cast<const bf16x8*>(&Kh[(size_t)((k0) + sr) * LDQK + sc]); sr_[i].ks1 = *reinterpret_cast<const bf16x8*>(&Kh[(size_t)((k0) + 32 + sr) * LDQK + sc]); } while (0)
; #define PSM(P0, P1, MN, AL, J) partialSM<MODE>(P0, P1, m_reg, MN, AL, relq + 64 * (J), relwmin + 64 * (J), relwmax + 64 * (J), lut)
; __device__ __forceinline__ void finishSM(f32x16& p0, f32x16& p1, float alpha, float& l_reg, bf16x8& pa0, bf16x8& pa1, bf16x8& pa2, bf16x8& pa3) {
;     ...
;   for (int r = 0; r < 16; ++r) p1[r] = __builtin_amdgcn_exp2f(p1[r]);
;   float ps = 0;
; #pragma unroll
;   for (int r = 0; r < 16; ++r) ps += p0[r];
; #pragma unroll
;   for (int r = 0; r < 16; ++r) ps += p1[r];
;   { auto rr = __builtin_amdgcn_permlane32_swap(__float_as_uint(ps), __float_as_uint(ps), false, false);
;     ps = __uint_as_float(rr[0]) + __uint_as_float(rr[1]); }
;   l_reg = l_reg * alpha + ps;
;     ...
;   PK4(p0, 0, pa0); PK4(p0, 8, pa1); PK4(p1, 0, pa2); PK4(p1, 8, pa3);
; template <int MODE>
; __device__ __forceinline__ void attn_body(const bf16_t* __restrict__ Qb, const bf16_t* __restrict__ Kh, const bf16_t* __restrict__ Vh, int NT, int krel0,
;                                           char* lds, const float* __restrict__ lutg, const AttnEpi& E) {
;     ...
;   for (int j = 1; j + 1 < NT; j += 2) {
;     __syncthreads();
;     SBAR(); qkt<ND0, DOFF>(pB0, pB1, K_lds + oq, qr, r32, hi);
;     finishSM(pA0, pA1, alA, l_reg, pa0, pa1, pa2, pa3); SBAR();
;     SLOAD(SO, (j + 2) * 64); SBAR();
;     pv_d0(o, vb0 + op, pa0, pa1, pa2, pa3); PSM(pB0, pB1, mnB, alB, j);
.LBB0_79:
	s_mov_b32 s69, s0
	s_waitcnt vmcnt(0) lgkmcnt(0)
	s_barrier
	s_add_i32 m0, s69, s30
	s_nop 0
	global_load_lds_dwordx4 v130, s[26:27]
	s_add_i32 m0, m0, 0x400
	s_nop 0
	global_load_lds_dwordx4 v131, s[26:27]
	s_add_i32 m0, m0, 0xbc00
	s_nop 0
	global_load_lds_dwordx4 v132, s[28:29]
	s_add_i32 m0, m0, 0x400
	s_nop 0
	global_load_lds_dwordx4 v133, s[28:29]
	s_add_u32 s26, s26, 0x90000
	s_addc_u32 s27, s27, 0
	s_add_u32 s28, s28, 0x90000
	s_addc_u32 s29, s29, 0
	s_add_i32 s0, s71, 0
	v_add_u32_e32 v70, s0, v214
	ds_read_b128 v[66:69], v70 offset:49152
	ds_read_b128 v[70:73], v70 offset:57344
	v_add_u32_e32 v162, s0, v218
	ds_read_b128 v[230:233], v162 offset:49152
	ds_read_b128 v[234:237], v162 offset:57344
	v_add_u32_e32 v162, s0, v219
	s_waitcnt lgkmcnt(3)
	v_mfma_f32_32x32x16_bf16 v[82:97], v[66:69], v[114:117], 0
	v_exp_f32_e32 v160, v160
	v_exp_f32_e32 v161, v161
	v_exp_f32_e32 v158, v158
	v_exp_f32_e32 v159, v159
	v_exp_f32_e32 v156, v156
	v_exp_f32_e32 v157, v157
	v_exp_f32_e32 v154, v154
	s_waitcnt lgkmcnt(2)
	v_mfma_f32_32x32x16_bf16 v[66:81], v[70:73], v[114:117], 0
	v_exp_f32_e32 v155, v155
	v_exp_f32_e32 v152, v152
	v_exp_f32_e32 v153, v153
	v_exp_f32_e32 v150, v150
	v_exp_f32_e32 v151, v151
	v_exp_f32_e32 v148, v148
	v_exp_f32_e32 v149, v149
	s_waitcnt lgkmcnt(1)
	v_mfma_f32_32x32x16_bf16 v[82:97], v[230:233], v[126:129], v[82:97]
	v_exp_f32_e32 v146, v146
	v_exp_f32_e32 v147, v147
	v_cvt_pk_bf16_f32 v163, v175, v177
	v_cvt_pk_bf16_f32 v229, v172, v174
	s_waitcnt lgkmcnt(0)
	v_mfma_f32_32x32x16_bf16 v[66:81], v[234:237], v[126:129], v[66:81]
	ds_read_b128 v[230:233], v162 offset:49152
	ds_read_b128 v[234:237], v162 offset:57344
	v_add_u32_e32 v162, s0, v216
	s_waitcnt lgkmcnt(1)
	v_mfma_f32_32x32x16_bf16 v[82:97], v[230:233], v[118:121], v[82:97]
	s_waitcnt lgkmcnt(0)
	v_mfma_f32_32x32x16_bf16 v[66:81], v[234:237], v[118:121], v[66:81]
	ds_read_b128 v[230:233], v162 offset:49152
	ds_read_b128 v[234:237], v162 offset:57344
	v_add_u32_e32 v162, s0, v217
	s_waitcnt lgkmcnt(1)
	v_mfma_f32_32x32x16_bf16 v[82:97], v[230:233], v[122:125], v[82:97]
	s_waitcnt lgkmcnt(0)
	v_mfma_f32_32x32x16_bf16 v[66:81], v[234:237], v[122:125], v[66:81]
	ds_read_b128 v[230:233], v162 offset:49152
	ds_read_b128 v[234:237], v162 offset:57344
	v_add_u32_e32 v162, s0, v215
	s_waitcnt lgkmcnt(1)
	v_mfma_f32_32x32x16_bf16 v[82:97], v[230:233], v[110:113], v[82:97]
	s_waitcnt lgkmcnt(0)
	v_mfma_f32_32x32x16_bf16 v[66:81], v[234:237], v[110:113], v[66:81]
	ds_read_b128 v[230:233], v162 offset:49152
	ds_read_b128 v[234:237], v162 offset:57344
	v_add_u32_e32 v162, s0, v220
	s_waitcnt lgkmcnt(1)
	v_mfma_f32_32x32x16_bf16 v[82:97], v[230:233], v[106:109], v[82:97]
	s_waitcnt lgkmcnt(0)
	v_mfma_f32_32x32x16_bf16 v[66:81], v[234:237], v[106:109], v[66:81]
	ds_read_b128 v[230:233], v162 offset:49152
	ds_read_b128 v[234:237], v162 offset:57344
	v_add_u32_e32 v162, s0, v221
	s_waitcnt lgkmcnt(1)
	v_mfma_f32_32x32x16_bf16 v[82:97], v[230:233], v[102:105], v[82:97]
	s_waitcnt lgkmcnt(0)
	v_mfma_f32_32x32x16_bf16 v[66:81], v[234:237], v[102:105], v[66:81]
	ds_read_b128 v[230:233], v162 offset:49152
	ds_read_b128 v[234:237], v162 offset:57344
	v_add_f32_e32 v162, v165, v164
	v_add_f32_e32 v162, v175, v162
	v_add_f32_e32 v162, v177, v162
	v_add_f32_e32 v162, v227, v162
	v_add_f32_e32 v162, v228, v162
	v_add_f32_e32 v162, v176, v162
	v_add_f32_e32 v162, v226, v162
	v_add_f32_e32 v162, v167, v162
	v_add_f32_e32 v162, v169, v162
	v_add_f32_e32 v162, v171, v162
	v_add_f32_e32 v162, v173, v162
	v_add_f32_e32 v162, v168, v162
	v_add_f32_e32 v162, v170, v162
	v_add_f32_e32 v162, v172, v162
	v_add_f32_e32 v162, v174, v162
	v_add_f32_e32 v162, v160, v162
	v_add_f32_e32 v162, v161, v162
	v_add_f32_e32 v162, v158, v162
	v_add_f32_e32 v162, v159, v162
	v_add_f32_e32 v162, v156, v162
	v_add_f32_e32 v162, v157, v162
	v_add_f32_e32 v162, v154, v162
	v_add_f32_e32 v162, v155, v162
	v_add_f32_e32 v162, v152, v162
	v_add_f32_e32 v162, v153, v162
	s_waitcnt lgkmcnt(1)
	v_mfma_f32_32x32x16_bf16 v[82:97], v[230:233], v[98:101], v[82:97]
	v_add_f32_e32 v162, v150, v162
	v_add_f32_e32 v162, v151, v162
	v_add_f32_e32 v162, v148, v162
	v_add_f32_e32 v162, v149, v162
	v_add_f32_e32 v162, v146, v162
	v_add_f32_e32 v223, v147, v162
	v_mov_b32_e32 v224, v223
	s_waitcnt lgkmcnt(0)
	v_mfma_f32_32x32x16_bf16 v[66:81], v[234:237], v[98:101], v[66:81]
	v_cvt_pk_bf16_f32 v162, v164, v165
	v_cvt_pk_bf16_f32 v164, v227, v228
	v_permlane32_swap_b32_e32 v223, v224
	v_cvt_pk_bf16_f32 v165, v176, v226
	v_permlane32_swap_b32_e32 v162, v164
	v_cvt_pk_bf16_f32 v226, v167, v169
	v_cvt_pk_bf16_f32 v227, v171, v173
	v_cvt_pk_bf16_f32 v228, v168, v170
	v_cvt_pk_bf16_f32 v168, v160, v161
	v_cvt_pk_bf16_f32 v169, v158, v159
	v_cvt_pk_bf16_f32 v170, v156, v157
	v_cvt_pk_bf16_f32 v171, v154, v155
	v_cvt_pk_bf16_f32 v172, v152, v153
	v_cvt_pk_bf16_f32 v173, v150, v151
	v_cvt_pk_bf16_f32 v174, v148, v149
	v_cvt_pk_bf16_f32 v175, v146, v147
	v_permlane32_swap_b32_e32 v163, v165
	v_permlane32_swap_b32_e32 v226, v228
	v_permlane32_swap_b32_e32 v227, v229
	v_permlane32_swap_b32_e32 v168, v170
	v_permlane32_swap_b32_e32 v169, v171
	v_permlane32_swap_b32_e32 v172, v174
	v_permlane32_swap_b32_e32 v173, v175
	v_add_u32_e32 v208, s68, v209
	ds_read_b64_tr_b16 v[230:231], v208 offset:0
	ds_read_b64_tr_b16 v[232:233], v208 offset:0x800
	ds_read_b64_tr_b16 v[234:235], v208 offset:0x1000
	ds_read_b64_tr_b16 v[236:237], v208 offset:0x1800
	ds_read_b64_tr_b16 v[238:239], v208 offset:0x2000
	ds_read_b64_tr_b16 v[240:241], v208 offset:0x2800
	ds_read_b64_tr_b16 v[242:243], v208 offset:0x3000
	ds_read_b64_tr_b16 v[244:245], v208 offset:0x3800
	s_waitcnt lgkmcnt(0)
; #define SBAR() __builtin_amdgcn_sched_barrier(0)
; #define SWRITE(off, i) do { *(bf16x8*)(V_lds + (off) + vst0) = sr_[i].vs0;          \
;     *(bf16x8*)(V_lds + (off) + vst1) = sr_[i].vs1; int kc = sc * 2;               \
;     *(bf16x8*)(K_lds + (off) + KSWZ(sr, kc)) = sr_[i].ks0;                       \
;     *(bf16x8*)(K_lds + (off) + KSWZ(32 + sr, kc)) = sr_[i].ks1; } while (0)
; #define SWAIT() asm volatile("s_waitcnt vmcnt(4)" ::: "memory")
; #define RESC(a) do { if (__any((a) < 1.f)) { if (hi == 0) al_l[r32] = (a); asm volatile("s_waitcnt lgkmcnt(0)" ::: "memory"); \
;     _Pragma("unroll") for (int d = 0; d < 4; ++d) _Pragma("unroll") for (int r = 0; r < 16; ++r) o[d][r] *= al_l[crow(r, hi)]; } } while (0)
; #define PSM(P0, P1, MN, AL, J) partialSM<MODE>(P0, P1, m_reg, MN, AL, relq + 64 * (J), relwmin + 64 * (J), relwmax + 64 * (J), lut)
; template <int MODE>
; __device__ __forceinline__ void partialSM(f32x16& p0, f32x16& p1, float& m_reg, float& mn, float& alpha, int relh, int relw_min, int relw_max, const float* lut) {
;     ...
;     for (int r = 0; r < 16; ++r) p0[r] = fmaf(p0[r], C, mnC);
; #pragma unroll
;     for (int r = 0; r < 16; ++r) p1[r] = fmaf(p1[r], C, mnC);
; #pragma unroll
;     for (int r = 0; r < 16; ++r) p0[r] = __builtin_amdgcn_exp2f(p0[r]);
; template <int MODE>
; __device__ __forceinline__ void attn_body(const bf16_t* __restrict__ Qb, const bf16_t* __restrict__ Kh, const bf16_t* __restrict__ Vh, int NT, int krel0,
;                                           char* lds, const float* __restrict__ lutg, const AttnEpi& E) {
;     ...
;     pv_d0(o, vb0 + op, pa0, pa1, pa2, pa3); PSM(pB0, pB1, mnB, alB, j);
;     SWAIT(); SWRITE(ow, SE);
;     RESC(alB);
;     { const int t = op; op = oq; oq = ow; ow = t; }
;     __syncthreads();
;     SBAR(); qkt<ND0, DOFF>(pA0, pA1, K_lds + oq, qr, r32, hi);
	s_nop 0
	v_mfma_f32_32x32x16_bf16 v[18:33], v[162:165], v[230:233], v[18:33]
	ds_read_b64_tr_b16 v[230:231], v208 offset:0x200
	ds_read_b64_tr_b16 v[232:233], v208 offset:0xa00
	v_mfma_f32_32x32x16_bf16 v[18:33], v[226:229], v[234:237], v[18:33]
	ds_read_b64_tr_b16 v[234:235], v208 offset:0x1200
	ds_read_b64_tr_b16 v[236:237], v208 offset:0x1a00
	v_mfma_f32_32x32x16_bf16 v[18:33], v[168:171], v[238:241], v[18:33]
	ds_read_b64_tr_b16 v[238:239], v208 offset:0x2200
	ds_read_b64_tr_b16 v[240:241], v208 offset:0x2a00
	v_mfma_f32_32x32x16_bf16 v[18:33], v[172:175], v[242:245], v[18:33]
	ds_read_b64_tr_b16 v[242:243], v208 offset:0x3200
	ds_read_b64_tr_b16 v[244:245], v208 offset:0x3a00
	s_waitcnt lgkmcnt(0)
	v_mfma_f32_32x32x16_bf16 v[50:65], v[162:165], v[230:233], v[50:65]
	ds_read_b64_tr_b16 v[230:231], v208 offset:0x400
	ds_read_b64_tr_b16 v[232:233], v208 offset:0xc00
	v_mfma_f32_32x32x16_bf16 v[50:65], v[226:229], v[234:237], v[50:65]
	ds_read_b64_tr_b16 v[234:235], v208 offset:0x1400
	ds_read_b64_tr_b16 v[236:237], v208 offset:0x1c00
	v_mfma_f32_32x32x16_bf16 v[50:65], v[168:171], v[238:241], v[50:65]
	ds_read_b64_tr_b16 v[238:239], v208 offset:0x2400
	ds_read_b64_tr_b16 v[240:241], v208 offset:0x2c00
	v_mfma_f32_32x32x16_bf16 v[50:65], v[172:175], v[242:245], v[50:65]
	ds_read_b64_tr_b16 v[242:243], v208 offset:0x3400
	ds_read_b64_tr_b16 v[244:245], v208 offset:0x3c00
	s_waitcnt lgkmcnt(0)
	v_mfma_f32_32x32x16_bf16 v[34:49], v[162:165], v[230:233], v[34:49]
	ds_read_b64_tr_b16 v[230:231], v208 offset:0x600
	ds_read_b64_tr_b16 v[232:233], v208 offset:0xe00
	v_mfma_f32_32x32x16_bf16 v[34:49], v[226:229], v[234:237], v[34:49]
	ds_read_b64_tr_b16 v[234:235], v208 offset:0x1600
	ds_read_b64_tr_b16 v[236:237], v208 offset:0x1e00
	v_mfma_f32_32x32x16_bf16 v[34:49], v[168:171], v[238:241], v[34:49]
	ds_read_b64_tr_b16 v[238:239], v208 offset:0x2600
	ds_read_b64_tr_b16 v[240:241], v208 offset:0x2e00
	v_mfma_f32_32x32x16_bf16 v[34:49], v[172:175], v[242:245], v[34:49]
	ds_read_b64_tr_b16 v[242:243], v208 offset:0x3600
	ds_read_b64_tr_b16 v[244:245], v208 offset:0x3e00
	s_waitcnt lgkmcnt(0)
	v_mfma_f32_32x32x16_bf16 v[2:17], v[162:165], v[230:233], v[2:17]
	v_mfma_f32_32x32x16_bf16 v[2:17], v[226:229], v[234:237], v[2:17]
	v_mfma_f32_32x32x16_bf16 v[2:17], v[168:171], v[238:241], v[2:17]
	v_mfma_f32_32x32x16_bf16 v[2:17], v[172:175], v[242:245], v[2:17]
	s_add_i32 s72, s69, 0
.LBB0_83:
	v_mov_b32_e32 v226, v166
	v_mul_f32_e32 v170, 0xbe0293ee, v226
	v_fmamk_f32 v82, v82, 0x3e0293ee, v170
	v_fmamk_f32 v83, v83, 0x3e0293ee, v170
	v_fmamk_f32 v84, v84, 0x3e0293ee, v170
	v_fmamk_f32 v85, v85, 0x3e0293ee, v170
	v_fmamk_f32 v86, v86, 0x3e0293ee, v170
	v_fmamk_f32 v87, v87, 0x3e0293ee, v170
	v_fmamk_f32 v88, v88, 0x3e0293ee, v170
	v_fmamk_f32 v89, v89, 0x3e0293ee, v170
	v_fmamk_f32 v90, v90, 0x3e0293ee, v170
	v_fmamk_f32 v91, v91, 0x3e0293ee, v170
	v_fmamk_f32 v92, v92, 0x3e0293ee, v170
	v_fmamk_f32 v93, v93, 0x3e0293ee, v170
	v_fmamk_f32 v94, v94, 0x3e0293ee, v170
	v_fmamk_f32 v95, v95, 0x3e0293ee, v170
	v_fmamk_f32 v96, v96, 0x3e0293ee, v170
	v_fmamk_f32 v97, v97, 0x3e0293ee, v170
	v_fmamk_f32 v171, v66, 0x3e0293ee, v170
	v_fmamk_f32 v172, v67, 0x3e0293ee, v170
	v_fmamk_f32 v173, v68, 0x3e0293ee, v170
	v_fmamk_f32 v174, v69, 0x3e0293ee, v170
	v_fmamk_f32 v175, v70, 0x3e0293ee, v170
	v_fmamk_f32 v176, v71, 0x3e0293ee, v170
	v_fmamk_f32 v177, v72, 0x3e0293ee, v170
	v_fmamk_f32 v227, v73, 0x3e0293ee, v170
	v_fmamk_f32 v228, v74, 0x3e0293ee, v170
	v_fmamk_f32 v229, v75, 0x3e0293ee, v170
	v_fmamk_f32 v230, v76, 0x3e0293ee, v170
	v_fmamk_f32 v231, v77, 0x3e0293ee, v170
	v_fmamk_f32 v232, v78, 0x3e0293ee, v170
	v_fmamk_f32 v233, v79, 0x3e0293ee, v170
	v_fmamk_f32 v234, v80, 0x3e0293ee, v170
	v_fmac_f32_e32 v170, 0x3e0293ee, v81
	v_exp_f32_e32 v235, v82
	v_exp_f32_e32 v236, v83
	v_exp_f32_e32 v237, v84
	v_exp_f32_e32 v238, v85
	v_exp_f32_e32 v239, v86
	v_exp_f32_e32 v240, v87
	v_exp_f32_e32 v241, v88
	v_exp_f32_e32 v242, v89
	v_exp_f32_e32 v243, v90
	v_exp_f32_e32 v244, v91
	v_exp_f32_e32 v245, v92
	v_exp_f32_e32 v246, v93
	v_exp_f32_e32 v247, v94
	v_exp_f32_e32 v248, v95
	v_exp_f32_e32 v249, v96
	v_exp_f32_e32 v250, v97
	s_waitcnt vmcnt(0) lgkmcnt(0)
	s_barrier
	s_add_i32 m0, s68, s30
	s_nop 0
	global_load_lds_dwordx4 v130, s[26:27]
	s_add_i32 m0, m0, 0x400
	s_nop 0
	global_load_lds_dwordx4 v131, s[26:27]
	s_add_i32 m0, m0, 0xbc00
	s_nop 0
	global_load_lds_dwordx4 v132, s[28:29]
	s_add_i32 m0, m0, 0x400
	s_nop 0
	global_load_lds_dwordx4 v133, s[28:29]
	s_add_u32 s26, s26, 0x90000
	s_addc_u32 s27, s27, 0
	s_add_u32 s28, s28, 0x90000
	s_addc_u32 s29, s29, 0
	v_add_u32_e32 v70, s72, v214
	ds_read_b128 v[66:69], v70 offset:49152
	ds_read_b128 v[70:73], v70 offset:57344
	v_add_u32_e32 v166, s72, v218
	ds_read_b128 v[162:165], v166 offset:49152
	ds_read_b128 v[166:169], v166 offset:57344
	v_exp_f32_e32 v171, v171
	s_waitcnt lgkmcnt(3)
	v_mfma_f32_32x32x16_bf16 v[82:97], v[66:69], v[114:117], 0
	v_exp_f32_e32 v172, v172
	v_exp_f32_e32 v173, v173
	v_exp_f32_e32 v174, v174
	v_exp_f32_e32 v175, v175
	v_exp_f32_e32 v176, v176
	v_exp_f32_e32 v177, v177
	v_exp_f32_e32 v227, v227
	s_waitcnt lgkmcnt(2)
	v_mfma_f32_32x32x16_bf16 v[66:81], v[70:73], v[114:117], 0
	v_exp_f32_e32 v228, v228
	v_exp_f32_e32 v251, v229
	v_exp_f32_e32 v195, v230
	v_exp_f32_e32 v231, v231
	v_exp_f32_e32 v232, v232
	v_exp_f32_e32 v233, v233
	v_exp_f32_e32 v234, v234
	s_waitcnt lgkmcnt(1)
	v_mfma_f32_32x32x16_bf16 v[82:97], v[162:165], v[126:129], v[82:97]
	v_exp_f32_e32 v194, v170
	v_cvt_pk_bf16_f32 v170, v171, v172
	s_waitcnt lgkmcnt(0)
; #define SBAR() __builtin_amdgcn_sched_barrier(0)
; #define SLOAD(i, k0) do { sr_[i].vs0 = *reinterpret_cast<const bf16x8*>(&Vh[(size_t)((k0) + sr) * LDQK + sc]); sr_[i].vs1 = *reinterpret_cast<const bf16x8*>(&Vh[(size_t)((k0) + 32 + sr) * LDQK + sc]); \
;     sr_[i].ks0 = *reinterpret_cast<const bf16x8*>(&Kh[(size_t)((k0) + sr) * LDQK + sc]); sr_[i].ks1 = *reinterpret_cast<const bf16x8*>(&Kh[(size_t)((k0) + 32 + sr) * LDQK + sc]); } while (0)
; #define PSM(P0, P1, MN, AL, J) partialSM<MODE>(P0, P1, m_reg, MN, AL, relq + 64 * (J), relwmin + 64 * (J), relwmax + 64 * (J), lut)
; __device__ __forceinline__ void finishSM(f32x16& p0, f32x16& p1, float alpha, float& l_reg, bf16x8& pa0, bf16x8& pa1, bf16x8& pa2, bf16x8& pa3) {
;     ...
;   for (int r = 0; r < 16; ++r) p1[r] = __builtin_amdgcn_exp2f(p1[r]);
;   float ps = 0;
; #pragma unroll
;   for (int r = 0; r < 16; ++r) ps += p0[r];
; #pragma unroll
;   for (int r = 0; r < 16; ++r) ps += p1[r];
;   { auto rr = __builtin_amdgcn_permlane32_swap(__float_as_uint(ps), __float_as_uint(ps), false, false);
;     ps = __uint_as_float(rr[0]) + __uint_as_float(rr[1]); }
;   l_reg = l_reg * alpha + ps;
;     ...
;   PK4(p0, 0, pa0); PK4(p0, 8, pa1); PK4(p1, 0, pa2); PK4(p1, 8, pa3);
; template <int MODE>
; __device__ __forceinline__ void attn_body(const bf16_t* __restrict__ Qb, const bf16_t* __restrict__ Kh, const bf16_t* __restrict__ Vh, int NT, int krel0,
;                                           char* lds, const float* __restrict__ lutg, const AttnEpi& E) {
;     ...
;     SBAR(); qkt<ND0, DOFF>(pA0, pA1, K_lds + oq, qr, r32, hi);
;     finishSM(pB0, pB1, alB, l_reg, pa0, pa1, pa2, pa3); SBAR();
;     if (j + 3 < NT) SLOAD(SE, (j + 3) * 64); SBAR();
;     pv_d0(o, vb0 + op, pa0, pa1, pa2, pa3); PSM(pA0, pA1, mnA, alA, j + 1);
	v_mfma_f32_32x32x16_bf16 v[66:81], v[166:169], v[126:129], v[66:81]
	v_add_u32_e32 v166, s72, v219
	ds_read_b128 v[162:165], v166 offset:49152
	ds_read_b128 v[166:169], v166 offset:57344
	s_waitcnt lgkmcnt(1)
	v_mfma_f32_32x32x16_bf16 v[82:97], v[162:165], v[118:121], v[82:97]
	s_waitcnt lgkmcnt(0)
	v_mfma_f32_32x32x16_bf16 v[66:81], v[166:169], v[118:121], v[66:81]
	v_add_u32_e32 v166, s72, v216
	ds_read_b128 v[162:165], v166 offset:49152
	ds_read_b128 v[166:169], v166 offset:57344
	s_waitcnt lgkmcnt(1)
	v_mfma_f32_32x32x16_bf16 v[82:97], v[162:165], v[122:125], v[82:97]
	s_waitcnt lgkmcnt(0)
	v_mfma_f32_32x32x16_bf16 v[66:81], v[166:169], v[122:125], v[66:81]
	v_add_u32_e32 v166, s72, v217
	ds_read_b128 v[162:165], v166 offset:49152
	ds_read_b128 v[166:169], v166 offset:57344
	s_waitcnt lgkmcnt(1)
	v_mfma_f32_32x32x16_bf16 v[82:97], v[162:165], v[110:113], v[82:97]
	s_waitcnt lgkmcnt(0)
	v_mfma_f32_32x32x16_bf16 v[66:81], v[166:169], v[110:113], v[66:81]
	v_add_u32_e32 v166, s72, v215
	ds_read_b128 v[162:165], v166 offset:49152
	ds_read_b128 v[166:169], v166 offset:57344
	s_waitcnt lgkmcnt(1)
	v_mfma_f32_32x32x16_bf16 v[82:97], v[162:165], v[106:109], v[82:97]
	s_waitcnt lgkmcnt(0)
	v_mfma_f32_32x32x16_bf16 v[66:81], v[166:169], v[106:109], v[66:81]
	v_add_u32_e32 v166, s72, v220
	ds_read_b128 v[162:165], v166 offset:49152
	ds_read_b128 v[166:169], v166 offset:57344
	s_waitcnt lgkmcnt(1)
	v_mfma_f32_32x32x16_bf16 v[82:97], v[162:165], v[102:105], v[82:97]
	s_waitcnt lgkmcnt(0)
	v_mfma_f32_32x32x16_bf16 v[66:81], v[166:169], v[102:105], v[66:81]
	v_add_u32_e32 v166, s72, v221
	ds_read_b128 v[162:165], v166 offset:49152
	ds_read_b128 v[166:169], v166 offset:57344
	s_waitcnt lgkmcnt(1)
	v_mfma_f32_32x32x16_bf16 v[82:97], v[162:165], v[98:101], v[82:97]
	v_add_f32_e32 v162, v236, v235
	v_add_f32_e32 v162, v237, v162
	v_add_f32_e32 v162, v238, v162
	v_add_f32_e32 v162, v239, v162
	v_add_f32_e32 v162, v240, v162
	v_add_f32_e32 v162, v241, v162
	v_add_f32_e32 v162, v242, v162
	v_add_f32_e32 v162, v243, v162
	v_add_f32_e32 v162, v244, v162
	v_add_f32_e32 v162, v245, v162
	v_add_f32_e32 v162, v246, v162
	v_add_f32_e32 v162, v247, v162
	v_add_f32_e32 v162, v248, v162
	v_add_f32_e32 v162, v249, v162
	v_add_f32_e32 v162, v250, v162
	v_add_f32_e32 v162, v171, v162
	v_add_f32_e32 v162, v172, v162
	v_add_f32_e32 v162, v173, v162
	v_add_f32_e32 v162, v174, v162
	v_add_f32_e32 v162, v175, v162
	v_add_f32_e32 v162, v176, v162
	v_add_f32_e32 v162, v177, v162
	v_add_f32_e32 v162, v227, v162
	v_add_f32_e32 v162, v228, v162
	v_add_f32_e32 v162, v251, v162
	s_waitcnt lgkmcnt(0)
	v_mfma_f32_32x32x16_bf16 v[66:81], v[166:169], v[98:101], v[66:81]
	v_add_f32_e32 v162, v195, v162
	v_add_f32_e32 v162, v231, v162
	v_add_f32_e32 v162, v232, v162
	v_add_f32_e32 v162, v233, v162
	v_add_f32_e32 v162, v234, v162
	v_add_f32_e32 v229, v194, v162
	v_mov_b32_e32 v230, v229
	v_cvt_pk_bf16_f32 v162, v235, v236
	v_cvt_pk_bf16_f32 v163, v237, v238
	v_cvt_pk_bf16_f32 v164, v239, v240
	v_cvt_pk_bf16_f32 v165, v241, v242
	v_cvt_pk_bf16_f32 v166, v243, v244
	v_cvt_pk_bf16_f32 v167, v245, v246
	v_cvt_pk_bf16_f32 v168, v247, v248
	v_cvt_pk_bf16_f32 v169, v249, v250
	v_cvt_pk_bf16_f32 v171, v173, v174
	v_cvt_pk_bf16_f32 v172, v175, v176
	v_cvt_pk_bf16_f32 v173, v177, v227
	v_cvt_pk_bf16_f32 v174, v228, v251
	v_cvt_pk_bf16_f32 v175, v195, v231
	v_cvt_pk_bf16_f32 v176, v232, v233
	v_cvt_pk_bf16_f32 v177, v234, v194
	v_permlane32_swap_b32_e32 v229, v230
	v_permlane32_swap_b32_e32 v162, v164
	v_permlane32_swap_b32_e32 v163, v165
	v_permlane32_swap_b32_e32 v166, v168
	v_permlane32_swap_b32_e32 v167, v169
	v_permlane32_swap_b32_e32 v170, v172
	v_permlane32_swap_b32_e32 v171, v173
	v_permlane32_swap_b32_e32 v174, v176
	v_permlane32_swap_b32_e32 v175, v177
.LBB0_85:
	v_add_u32_e32 v194, s71, v209
	ds_read_b64_tr_b16 v[232:233], v194 offset:0
	ds_read_b64_tr_b16 v[234:235], v194 offset:0x800
	ds_read_b64_tr_b16 v[236:237], v194 offset:0x1000
	ds_read_b64_tr_b16 v[238:239], v194 offset:0x1800
	ds_read_b64_tr_b16 v[240:241], v194 offset:0x2000
	ds_read_b64_tr_b16 v[242:243], v194 offset:0x2800
	ds_read_b64_tr_b16 v[244:245], v194 offset:0x3000
	ds_read_b64_tr_b16 v[246:247], v194 offset:0x3800
	s_waitcnt lgkmcnt(0)
	s_nop 0
	v_mfma_f32_32x32x16_bf16 v[18:33], v[162:165], v[232:235], v[18:33]
	ds_read_b64_tr_b16 v[232:233], v194 offset:0x200
	ds_read_b64_tr_b16 v[234:235], v194 offset:0xa00
	v_mfma_f32_32x32x16_bf16 v[18:33], v[166:169], v[236:239], v[18:33]
	ds_read_b64_tr_b16 v[236:237], v194 offset:0x1200
	ds_read_b64_tr_b16 v[238:239], v194 offset:0x1a00
	v_mfma_f32_32x32x16_bf16 v[18:33], v[170:173], v[240:243], v[18:33]
	ds_read_b64_tr_b16 v[240:241], v194 offset:0x2200
	ds_read_b64_tr_b16 v[242:243], v194 offset:0x2a00
	v_mfma_f32_32x32x16_bf16 v[18:33], v[174:177], v[244:247], v[18:33]
	ds_read_b64_tr_b16 v[244:245], v194 offset:0x3200
	ds_read_b64_tr_b16 v[246:247], v194 offset:0x3a00
	s_waitcnt lgkmcnt(0)
	v_mfma_f32_32x32x16_bf16 v[50:65], v[162:165], v[232:235], v[50:65]
	ds_read_b64_tr_b16 v[232:233], v194 offset:0x400
	ds_read_b64_tr_b16 v[234:235], v194 offset:0xc00
	v_mfma_f32_32x32x16_bf16 v[50:65], v[166:169], v[236:239], v[50:65]
	ds_read_b64_tr_b16 v[236:237], v194 offset:0x1400
	ds_read_b64_tr_b16 v[238:239], v194 offset:0x1c00
	v_mfma_f32_32x32x16_bf16 v[50:65], v[170:173], v[240:243], v[50:65]
	ds_read_b64_tr_b16 v[240:241], v194 offset:0x2400
	ds_read_b64_tr_b16 v[242:243], v194 offset:0x2c00
	v_mfma_f32_32x32x16_bf16 v[50:65], v[174:177], v[244:247], v[50:65]
	ds_read_b64_tr_b16 v[244:245], v194 offset:0x3400
	ds_read_b64_tr_b16 v[246:247], v194 offset:0x3c00
	s_waitcnt lgkmcnt(0)
	v_mfma_f32_32x32x16_bf16 v[34:49], v[162:165], v[232:235], v[34:49]
	ds_read_b64_tr_b16 v[232:233], v194 offset:0x600
	ds_read_b64_tr_b16 v[234:235], v194 offset:0xe00
	v_mfma_f32_32x32x16_bf16 v[34:49], v[166:169], v[236:239], v[34:49]
	ds_read_b64_tr_b16 v[236:237], v194 offset:0x1600
	ds_read_b64_tr_b16 v[238:239], v194 offset:0x1e00
	v_mfma_f32_32x32x16_bf16 v[34:49], v[170:173], v[240:243], v[34:49]
	ds_read_b64_tr_b16 v[240:241], v194 offset:0x2600
	ds_read_b64_tr_b16 v[242:243], v194 offset:0x2e00
	v_mfma_f32_32x32x16_bf16 v[34:49], v[174:177], v[244:247], v[34:49]
	ds_read_b64_tr_b16 v[244:245], v194 offset:0x3600
	ds_read_b64_tr_b16 v[246:247], v194 offset:0x3e00
	s_waitcnt lgkmcnt(0)
	v_mfma_f32_32x32x16_bf16 v[2:17], v[162:165], v[232:235], v[2:17]
	v_mfma_f32_32x32x16_bf16 v[2:17], v[166:169], v[236:239], v[2:17]
	v_mfma_f32_32x32x16_bf16 v[2:17], v[170:173], v[240:243], v[2:17]
	v_mfma_f32_32x32x16_bf16 v[2:17], v[174:177], v[244:247], v[2:17]
	s_add_i32 s72, s68, 0
; #define SBAR() __builtin_amdgcn_sched_barrier(0)
; #define SWRITE(off, i) do { *(bf16x8*)(V_lds + (off) + vst0) = sr_[i].vs0;          \
;     *(bf16x8*)(V_lds + (off) + vst1) = sr_[i].vs1; int kc = sc * 2;               \
;     *(bf16x8*)(K_lds + (off) + KSWZ(sr, kc)) = sr_[i].ks0;                       \
;     *(bf16x8*)(K_lds + (off) + KSWZ(32 + sr, kc)) = sr_[i].ks1; } while (0)
; #define SWAIT() asm volatile("s_waitcnt vmcnt(4)" ::: "memory")
; #define RESC(a) do { if (__any((a) < 1.f)) { if (hi == 0) al_l[r32] = (a); asm volatile("s_waitcnt lgkmcnt(0)" ::: "memory"); \
;     _Pragma("unroll") for (int d = 0; d < 4; ++d) _Pragma("unroll") for (int r = 0; r < 16; ++r) o[d][r] *= al_l[crow(r, hi)]; } } while (0)
; #define PSM(P0, P1, MN, AL, J) partialSM<MODE>(P0, P1, m_reg, MN, AL, relq + 64 * (J), relwmin + 64 * (J), relwmax + 64 * (J), lut)
; template <int MODE>
; __device__ __forceinline__ void attn_body(const bf16_t* __restrict__ Qb, const bf16_t* __restrict__ Kh, const bf16_t* __restrict__ Vh, int NT, int krel0,
;                                           char* lds, const float* __restrict__ lutg, const AttnEpi& E) {
;     ...
;     pv_d0(o, vb0 + op, pa0, pa1, pa2, pa3); PSM(pA0, pA1, mnA, alA, j + 1);
;     SWAIT(); SWRITE(ow, SO);
;     RESC(alA);
;     { const int t = op; op = oq; oq = ow; ow = t; }
;   }
;   __syncthreads();
;   SBAR(); qkt<ND0, DOFF>(pB0, pB1, K_lds + oq, qr, r32, hi);
.LBB0_89:
	v_mov_b32_e32 v166, v226
	v_mul_f32_e32 v146, 0xbe0293ee, v166
	v_mov_b32_e32 v163, v146
	v_fmamk_f32 v82, v82, 0x3e0293ee, v146
	v_fmamk_f32 v83, v83, 0x3e0293ee, v146
	v_fmamk_f32 v84, v84, 0x3e0293ee, v146
	v_fmamk_f32 v85, v85, 0x3e0293ee, v146
	v_fmamk_f32 v86, v86, 0x3e0293ee, v146
	v_fmamk_f32 v87, v87, 0x3e0293ee, v146
	v_fmamk_f32 v88, v88, 0x3e0293ee, v146
	v_fmamk_f32 v89, v89, 0x3e0293ee, v146
	v_fmamk_f32 v90, v90, 0x3e0293ee, v146
	v_fmamk_f32 v91, v91, 0x3e0293ee, v146
	v_fmamk_f32 v92, v92, 0x3e0293ee, v146
	v_fmamk_f32 v93, v93, 0x3e0293ee, v146
	v_fmamk_f32 v94, v94, 0x3e0293ee, v146
	v_fmamk_f32 v95, v95, 0x3e0293ee, v146
	v_fmamk_f32 v96, v96, 0x3e0293ee, v146
	v_fmac_f32_e32 v163, 0x3e0293ee, v97
	v_exp_f32_e32 v164, v82
	v_exp_f32_e32 v165, v83
	v_exp_f32_e32 v175, v84
	v_exp_f32_e32 v177, v85
	v_exp_f32_e32 v227, v86
	v_exp_f32_e32 v228, v87
	v_exp_f32_e32 v176, v88
	v_exp_f32_e32 v226, v89
	v_exp_f32_e32 v167, v90
	v_exp_f32_e32 v169, v91
	v_exp_f32_e32 v171, v92
	v_exp_f32_e32 v173, v93
	v_exp_f32_e32 v168, v94
	v_exp_f32_e32 v170, v95
	v_exp_f32_e32 v172, v96
	v_exp_f32_e32 v174, v163
	v_fmamk_f32 v161, v67, 0x3e0293ee, v146
	v_fmamk_f32 v160, v66, 0x3e0293ee, v146
	v_add_f32_e32 v66, v223, v224
	v_add_f32_e32 v66, v207, v66
	v_add_f32_e32 v207, v229, v230
	s_add_i32 s0, s66, 2
	s_add_i32 s1, s66, -1
	v_fmamk_f32 v159, v69, 0x3e0293ee, v146
	v_fmamk_f32 v158, v68, 0x3e0293ee, v146
	v_fmamk_f32 v157, v71, 0x3e0293ee, v146
	v_fmamk_f32 v156, v70, 0x3e0293ee, v146
	v_fmamk_f32 v155, v73, 0x3e0293ee, v146
	v_fmamk_f32 v154, v72, 0x3e0293ee, v146
	v_fmamk_f32 v153, v75, 0x3e0293ee, v146
	v_fmamk_f32 v152, v74, 0x3e0293ee, v146
	v_fmamk_f32 v151, v77, 0x3e0293ee, v146
	v_fmamk_f32 v150, v76, 0x3e0293ee, v146
	v_fmamk_f32 v149, v79, 0x3e0293ee, v146
	v_fmamk_f32 v148, v78, 0x3e0293ee, v146
	v_fmamk_f32 v147, v81, 0x3e0293ee, v146
	v_fmamk_f32 v146, v80, 0x3e0293ee, v146
	v_add_f32_e32 v207, v66, v207
	s_cmp_ge_u32 s1, s70
	v_lshl_add_u64 v[190:191], v[190:191], 0, s[44:45]
	s_cbranch_scc1 .LBB0_91
	s_mov_b32 s66, s0
	s_mov_b32 s0, s71
	s_mov_b32 s71, s68
	s_mov_b32 s68, s69
	s_branch .LBB0_79
.LBB0_91:
	v_mov_b32_e32 v162, 1.0
	s_waitcnt vmcnt(0) lgkmcnt(0)
	s_barrier
	v_add_u32_e32 v70, s72, v214
	ds_read_b128 v[66:69], v70 offset:49152
	ds_read_b128 v[70:73], v70 offset:57344
	v_add_u32_e32 v130, s72, v218
	s_waitcnt lgkmcnt(1)
	v_mfma_f32_32x32x16_bf16 v[82:97], v[66:69], v[114:117], 0
	s_waitcnt lgkmcnt(0)
	v_mfma_f32_32x32x16_bf16 v[66:81], v[70:73], v[114:117], 0
	ds_read_b128 v[114:117], v130 offset:49152
	ds_read_b128 v[130:133], v130 offset:57344
	s_waitcnt lgkmcnt(1)
	v_mfma_f32_32x32x16_bf16 v[82:97], v[114:117], v[126:129], v[82:97]
	s_waitcnt lgkmcnt(0)
	v_mfma_f32_32x32x16_bf16 v[66:81], v[130:133], v[126:129], v[66:81]
	v_add_u32_e32 v126, s72, v219
	ds_read_b128 v[114:117], v126 offset:49152
	ds_read_b128 v[126:129], v126 offset:57344
	s_waitcnt lgkmcnt(1)
	v_mfma_f32_32x32x16_bf16 v[82:97], v[114:117], v[118:121], v[82:97]
	s_waitcnt lgkmcnt(0)
	v_mfma_f32_32x32x16_bf16 v[66:81], v[126:129], v[118:121], v[66:81]
	v_add_u32_e32 v118, s72, v216
	ds_read_b128 v[114:117], v118 offset:49152
	ds_read_b128 v[118:121], v118 offset:57344
	s_waitcnt lgkmcnt(1)
	v_mfma_f32_32x32x16_bf16 v[82:97], v[114:117], v[122:125], v[82:97]
	s_waitcnt lgkmcnt(0)
	v_mfma_f32_32x32x16_bf16 v[66:81], v[118:121], v[122:125], v[66:81]
	v_add_u32_e32 v118, s72, v217
	ds_read_b128 v[114:117], v118 offset:49152
	ds_read_b128 v[118:121], v118 offset:57344
	v_exp_f32_e32 v122, v146
	v_exp_f32_e32 v123, v147
	s_waitcnt lgkmcnt(1)
	v_mfma_f32_32x32x16_bf16 v[82:97], v[114:117], v[110:113], v[82:97]
	v_add_u32_e32 v114, s72, v215
	s_waitcnt lgkmcnt(0)
	v_mfma_f32_32x32x16_bf16 v[66:81], v[118:121], v[110:113], v[66:81]
	ds_read_b128 v[110:113], v114 offset:49152
	ds_read_b128 v[114:117], v114 offset:57344
	v_exp_f32_e32 v118, v150
	v_exp_f32_e32 v119, v151
	v_exp_f32_e32 v120, v148
	v_exp_f32_e32 v121, v149
	s_waitcnt lgkmcnt(1)
	v_mfma_f32_32x32x16_bf16 v[82:97], v[110:113], v[106:109], v[82:97]
	v_add_u32_e32 v110, s72, v220
	s_waitcnt lgkmcnt(0)
	v_mfma_f32_32x32x16_bf16 v[66:81], v[114:117], v[106:109], v[66:81]
	ds_read_b128 v[106:109], v110 offset:49152
	ds_read_b128 v[110:113], v110 offset:57344
	v_exp_f32_e32 v114, v154
	v_exp_f32_e32 v115, v155
	v_exp_f32_e32 v116, v152
	v_exp_f32_e32 v117, v153
	s_waitcnt lgkmcnt(1)
	v_mfma_f32_32x32x16_bf16 v[82:97], v[106:109], v[102:105], v[82:97]
	v_add_u32_e32 v106, s72, v221
	s_waitcnt lgkmcnt(0)
	v_mfma_f32_32x32x16_bf16 v[66:81], v[110:113], v[102:105], v[66:81]
	ds_read_b128 v[102:105], v106 offset:49152
	ds_read_b128 v[106:109], v106 offset:57344
	v_exp_f32_e32 v110, v158
	v_exp_f32_e32 v111, v159
	v_exp_f32_e32 v112, v156
	v_exp_f32_e32 v113, v157
	s_waitcnt lgkmcnt(1)
	v_mfma_f32_32x32x16_bf16 v[82:97], v[102:105], v[98:101], v[82:97]
	v_cvt_pk_bf16_f32 v102, v227, v228
	v_cvt_pk_bf16_f32 v103, v176, v226
	v_cvt_pk_bf16_f32 v104, v167, v169
	v_cvt_pk_bf16_f32 v105, v171, v173
	s_waitcnt lgkmcnt(0)
; #define SBAR() __builtin_amdgcn_sched_barrier(0)
; #define RESC(a) do { if (__any((a) < 1.f)) { if (hi == 0) al_l[r32] = (a); asm volatile("s_waitcnt lgkmcnt(0)" ::: "memory"); \
;     _Pragma("unroll") for (int d = 0; d < 4; ++d) _Pragma("unroll") for (int r = 0; r < 16; ++r) o[d][r] *= al_l[crow(r, hi)]; } } while (0)
; #define PSM(P0, P1, MN, AL, J) partialSM<MODE>(P0, P1, m_reg, MN, AL, relq + 64 * (J), relwmin + 64 * (J), relwmax + 64 * (J), lut)
; __device__ __forceinline__ void finishSM(f32x16& p0, f32x16& p1, float alpha, float& l_reg, bf16x8& pa0, bf16x8& pa1, bf16x8& pa2, bf16x8& pa3) {
;     ...
;   for (int r = 0; r < 16; ++r) p1[r] = __builtin_amdgcn_exp2f(p1[r]);
;   float ps = 0;
; #pragma unroll
;   for (int r = 0; r < 16; ++r) ps += p0[r];
; #pragma unroll
;   for (int r = 0; r < 16; ++r) ps += p1[r];
;   { auto rr = __builtin_amdgcn_permlane32_swap(__float_as_uint(ps), __float_as_uint(ps), false, false);
;     ps = __uint_as_float(rr[0]) + __uint_as_float(rr[1]); }
;   l_reg = l_reg * alpha + ps;
;     ...
;   PK4(p0, 0, pa0); PK4(p0, 8, pa1); PK4(p1, 0, pa2); PK4(p1, 8, pa3);
; template <int MODE>
; __device__ __forceinline__ void attn_body(const bf16_t* __restrict__ Qb, const bf16_t* __restrict__ Kh, const bf16_t* __restrict__ Vh, int NT, int krel0,
;                                           char* lds, const float* __restrict__ lutg, const AttnEpi& E) {
;     ...
;   SBAR(); qkt<ND0, DOFF>(pB0, pB1, K_lds + oq, qr, r32, hi);
;   finishSM(pA0, pA1, alA, l_reg, pa0, pa1, pa2, pa3); SBAR();
;   pv_d0(o, vb0 + op, pa0, pa1, pa2, pa3); PSM(pB0, pB1, mnB, alB, NT - 1);
;   RESC(alB);
	v_mfma_f32_32x32x16_bf16 v[66:81], v[106:109], v[98:101], v[66:81]
	v_add_f32_e32 v98, 0, v164
	v_add_f32_e32 v98, v165, v98
	v_add_f32_e32 v98, v175, v98
	v_add_f32_e32 v98, v177, v98
	v_add_f32_e32 v98, v227, v98
	v_add_f32_e32 v98, v228, v98
	v_add_f32_e32 v98, v176, v98
	v_add_f32_e32 v98, v226, v98
	v_add_f32_e32 v98, v167, v98
	v_add_f32_e32 v98, v169, v98
	v_add_f32_e32 v98, v171, v98
	v_add_f32_e32 v98, v173, v98
	v_exp_f32_e32 v108, v160
	v_add_f32_e32 v98, v168, v98
	v_exp_f32_e32 v109, v161
	v_add_f32_e32 v98, v170, v98
	v_add_f32_e32 v98, v172, v98
	v_add_f32_e32 v98, v174, v98
	v_add_f32_e32 v98, v108, v98
	v_add_f32_e32 v98, v109, v98
	v_add_f32_e32 v98, v110, v98
	v_add_f32_e32 v98, v111, v98
	v_add_f32_e32 v98, v112, v98
	v_add_f32_e32 v98, v113, v98
	v_add_f32_e32 v98, v114, v98
	v_add_f32_e32 v98, v115, v98
	v_add_f32_e32 v98, v116, v98
	v_add_f32_e32 v98, v117, v98
	v_add_f32_e32 v98, v118, v98
	v_add_f32_e32 v98, v119, v98
	v_add_f32_e32 v98, v120, v98
	v_add_f32_e32 v98, v121, v98
	v_add_f32_e32 v98, v122, v98
	v_add_f32_e32 v98, v123, v98
	v_mov_b32_e32 v99, v98
	v_cvt_pk_bf16_f32 v100, v164, v165
	v_cvt_pk_bf16_f32 v101, v175, v177
	v_permlane32_swap_b32_e32 v98, v99
	v_permlane32_swap_b32_e32 v100, v102
	v_permlane32_swap_b32_e32 v101, v103
	v_cvt_pk_bf16_f32 v106, v168, v170
	v_cvt_pk_bf16_f32 v107, v172, v174
	v_cvt_pk_bf16_f32 v108, v108, v109
	v_cvt_pk_bf16_f32 v109, v110, v111
	v_cvt_pk_bf16_f32 v110, v112, v113
	v_cvt_pk_bf16_f32 v111, v114, v115
	v_cvt_pk_bf16_f32 v112, v116, v117
	v_cvt_pk_bf16_f32 v113, v118, v119
	v_cvt_pk_bf16_f32 v114, v120, v121
	v_cvt_pk_bf16_f32 v115, v122, v123
	v_permlane32_swap_b32_e32 v104, v106
	v_permlane32_swap_b32_e32 v105, v107
	v_permlane32_swap_b32_e32 v108, v110
	v_permlane32_swap_b32_e32 v109, v111
	v_permlane32_swap_b32_e32 v112, v114
	v_permlane32_swap_b32_e32 v113, v115
	v_add_u32_e32 v132, s69, v209
	ds_read_b64_tr_b16 v[116:117], v132 offset:0
	ds_read_b64_tr_b16 v[118:119], v132 offset:0x800
	ds_read_b64_tr_b16 v[120:121], v132 offset:0x1000
	ds_read_b64_tr_b16 v[122:123], v132 offset:0x1800
	ds_read_b64_tr_b16 v[124:125], v132 offset:0x2000
	ds_read_b64_tr_b16 v[126:127], v132 offset:0x2800
	ds_read_b64_tr_b16 v[128:129], v132 offset:0x3000
	ds_read_b64_tr_b16 v[130:131], v132 offset:0x3800
	s_waitcnt lgkmcnt(0)
	s_nop 0
	v_mfma_f32_32x32x16_bf16 v[18:33], v[100:103], v[116:119], v[18:33]
	ds_read_b64_tr_b16 v[116:117], v132 offset:0x200
	ds_read_b64_tr_b16 v[118:119], v132 offset:0xa00
	v_mfma_f32_32x32x16_bf16 v[18:33], v[104:107], v[120:123], v[18:33]
	ds_read_b64_tr_b16 v[120:121], v132 offset:0x1200
	ds_read_b64_tr_b16 v[122:123], v132 offset:0x1a00
	v_mfma_f32_32x32x16_bf16 v[18:33], v[108:111], v[124:127], v[18:33]
	ds_read_b64_tr_b16 v[124:125], v132 offset:0x2200
	ds_read_b64_tr_b16 v[126:127], v132 offset:0x2a00
	v_mfma_f32_32x32x16_bf16 v[18:33], v[112:115], v[128:131], v[18:33]
	ds_read_b64_tr_b16 v[128:129], v132 offset:0x3200
	ds_read_b64_tr_b16 v[130:131], v132 offset:0x3a00
	s_waitcnt lgkmcnt(0)
	v_mfma_f32_32x32x16_bf16 v[50:65], v[100:103], v[116:119], v[50:65]
	ds_read_b64_tr_b16 v[116:117], v132 offset:0x400
	ds_read_b64_tr_b16 v[118:119], v132 offset:0xc00
	v_mfma_f32_32x32x16_bf16 v[50:65], v[104:107], v[120:123], v[50:65]
	ds_read_b64_tr_b16 v[120:121], v132 offset:0x1400
	ds_read_b64_tr_b16 v[122:123], v132 offset:0x1c00
	v_mfma_f32_32x32x16_bf16 v[50:65], v[108:111], v[124:127], v[50:65]
	ds_read_b64_tr_b16 v[124:125], v132 offset:0x2400
	ds_read_b64_tr_b16 v[126:127], v132 offset:0x2c00
	v_mfma_f32_32x32x16_bf16 v[50:65], v[112:115], v[128:131], v[50:65]
	ds_read_b64_tr_b16 v[128:129], v132 offset:0x3400
	ds_read_b64_tr_b16 v[130:131], v132 offset:0x3c00
	s_waitcnt lgkmcnt(0)
	v_mfma_f32_32x32x16_bf16 v[34:49], v[100:103], v[116:119], v[34:49]
	ds_read_b64_tr_b16 v[116:117], v132 offset:0x600
	ds_read_b64_tr_b16 v[118:119], v132 offset:0xe00
	v_mfma_f32_32x32x16_bf16 v[34:49], v[104:107], v[120:123], v[34:49]
	ds_read_b64_tr_b16 v[120:121], v132 offset:0x1600
	ds_read_b64_tr_b16 v[122:123], v132 offset:0x1e00
	v_mfma_f32_32x32x16_bf16 v[34:49], v[108:111], v[124:127], v[34:49]
	ds_read_b64_tr_b16 v[124:125], v132 offset:0x2600
	ds_read_b64_tr_b16 v[126:127], v132 offset:0x2e00
	v_mfma_f32_32x32x16_bf16 v[34:49], v[112:115], v[128:131], v[34:49]
	ds_read_b64_tr_b16 v[128:129], v132 offset:0x3600
	ds_read_b64_tr_b16 v[130:131], v132 offset:0x3e00
	s_waitcnt lgkmcnt(0)
	v_mfma_f32_32x32x16_bf16 v[2:17], v[100:103], v[116:119], v[2:17]
	v_max_f32_e32 v100, v83, v83
	v_max_f32_e32 v101, v82, v82
	v_max_f32_e32 v100, v101, v100
	v_max3_f32 v100, v100, v84, v85
	v_max3_f32 v100, v100, v86, v87
	v_max3_f32 v100, v100, v88, v89
	v_max3_f32 v100, v100, v90, v91
	v_max3_f32 v100, v100, v92, v93
	v_max3_f32 v100, v100, v94, v95
	v_mfma_f32_32x32x16_bf16 v[2:17], v[104:107], v[120:123], v[2:17]
	v_max3_f32 v100, v100, v96, v97
	v_max3_f32 v100, v100, v66, v67
	v_max3_f32 v100, v100, v68, v69
	v_max3_f32 v100, v100, v70, v71
	v_max3_f32 v100, v100, v72, v73
	v_max3_f32 v100, v100, v74, v75
	v_max3_f32 v100, v100, v76, v77
	v_max3_f32 v100, v100, v78, v79
	v_mfma_f32_32x32x16_bf16 v[2:17], v[108:111], v[124:127], v[2:17]
	v_max3_f32 v100, v100, v80, v81
	v_mov_b32_e32 v101, v100
	s_nop 1
	v_permlane32_swap_b32_e32 v100, v101
	v_max_f32_e32 v101, v101, v101
	v_max_f32_e32 v100, v100, v100
	v_max_f32_e32 v100, v100, v101
	v_sub_f32_e32 v101, v100, v166
	v_cmp_ge_f32_e32 vcc, s40, v101
	v_max_f32_e32 v101, v166, v166
	v_max_f32_e32 v101, v101, v100
	v_mfma_f32_32x32x16_bf16 v[2:17], v[112:115], v[128:131], v[2:17]
	v_sub_f32_e32 v100, v166, v101
	v_mul_f32_e32 v100, 0x3e0293ee, v100
	v_exp_f32_e32 v100, v100
	s_cmp_eq_u64 vcc, exec
	s_cselect_b64 s[0:1], -1, 0
	v_cndmask_b32_e64 v100, v100, 1.0, s[0:1]
	v_cmp_gt_f32_e32 vcc, 1.0, v100
	s_cbranch_vccz .LBB0_95
	s_and_saveexec_b64 s[56:57], s[6:7]
	ds_write_b32 v206, v100 offset:128
	s_or_b64 exec, exec, s[56:57]
	s_waitcnt lgkmcnt(0)
	ds_read_b128 v[102:105], v0 offset:224
	ds_read_b128 v[106:109], v0 offset:192
	ds_read_b128 v[110:113], v0 offset:160
	ds_read_b128 v[114:117], v0 offset:128
	s_waitcnt lgkmcnt(3)
	v_pk_mul_f32 v[32:33], v[32:33], v[104:105]
	s_waitcnt lgkmcnt(2)
	v_pk_mul_f32 v[28:29], v[28:29], v[108:109]
	s_waitcnt lgkmcnt(1)
	v_pk_mul_f32 v[24:25], v[24:25], v[112:113]
	s_waitcnt lgkmcnt(0)
	v_pk_mul_f32 v[20:21], v[20:21], v[116:117]
	v_pk_mul_f32 v[30:31], v[30:31], v[102:103]
	v_pk_mul_f32 v[26:27], v[26:27], v[106:107]
	v_pk_mul_f32 v[22:23], v[22:23], v[110:111]
	v_pk_mul_f32 v[18:19], v[18:19], v[114:115]
	v_pk_mul_f32 v[64:65], v[64:65], v[104:105]
	v_pk_mul_f32 v[60:61], v[60:61], v[108:109]
	v_pk_mul_f32 v[56:57], v[56:57], v[112:113]
	v_pk_mul_f32 v[52:53], v[52:53], v[116:117]
	v_pk_mul_f32 v[62:63], v[62:63], v[102:103]
	v_pk_mul_f32 v[58:59], v[58:59], v[106:107]
	v_pk_mul_f32 v[54:55], v[54:55], v[110:111]
	v_pk_mul_f32 v[50:51], v[50:51], v[114:115]
	v_pk_mul_f32 v[48:49], v[48:49], v[104:105]
	v_pk_mul_f32 v[44:45], v[44:45], v[108:109]
	v_pk_mul_f32 v[40:41], v[40:41], v[112:113]
	v_pk_mul_f32 v[36:37], v[36:37], v[116:117]
	v_pk_mul_f32 v[46:47], v[46:47], v[102:103]
	v_pk_mul_f32 v[42:43], v[42:43], v[106:107]
	v_pk_mul_f32 v[38:39], v[38:39], v[110:111]
	v_pk_mul_f32 v[34:35], v[34:35], v[114:115]
	v_pk_mul_f32 v[16:17], v[16:17], v[104:105]
	v_pk_mul_f32 v[12:13], v[12:13], v[108:109]
	v_pk_mul_f32 v[8:9], v[8:9], v[112:113]
	v_pk_mul_f32 v[4:5], v[4:5], v[116:117]
	v_pk_mul_f32 v[14:15], v[14:15], v[102:103]
	v_pk_mul_f32 v[10:11], v[10:11], v[106:107]
	v_pk_mul_f32 v[6:7], v[6:7], v[110:111]
	v_pk_mul_f32 v[2:3], v[2:3], v[114:115]
